# GEMM K-loops: LDS-DMA uses the SGPR-base + 32-bit VGPR-offset form for 12 of 16 loads per iteration; 8 64-bit VALU address adds removed per iteration
# speedup vs baseline: 1.0042x; 1.0042x over previous
.LBB0_220:
	ds_read_b128 v[148:151], v173
	ds_read_b128 v[152:155], v173 offset:1024
	ds_read_b128 v[156:159], v173 offset:2048
	ds_read_b128 v[160:163], v173 offset:3072
	ds_read_b128 v[164:167], v174
	ds_read_b128 v[180:183], v174 offset:1024
	ds_read_b128 v[184:187], v174 offset:2048
	ds_read_b128 v[188:191], v174 offset:3072
	s_add_u32 s52, s50, 0xfffc0080
	s_addc_u32 s53, s51, -1
	s_cmp_eq_u32 s66, 12
	s_cselect_b32 s55, s9, s53
	s_cselect_b32 s54, s11, s52
	s_cselect_b32 s53, s20, s45
	s_cselect_b32 s52, s33, s43
	s_add_i32 m0, s35, 0xc000
	ds_read_b128 v[192:195], v175
	ds_read_b128 v[196:199], v175 offset:1024
	ds_read_b128 v[204:207], v175 offset:2048
	ds_read_b128 v[208:211], v175 offset:3072
	ds_read_b128 v[212:215], v175 offset:4096
	ds_read_b128 v[216:219], v175 offset:5120
	ds_read_b128 v[220:223], v175 offset:6144
	ds_read_b128 v[224:227], v175 offset:7168
	global_load_lds_dwordx4 v140, s[50:51]
	s_add_i32 m0, s35, 0xe000
	s_nop 0
	global_load_lds_dwordx4 v142, s[50:51]
	s_waitcnt vmcnt(8)
	s_waitcnt lgkmcnt(0)
	s_barrier
	s_setprio 1
	s_waitcnt lgkmcnt(0)
	v_mfma_f32_16x16x32_bf16 v[124:127], v[148:151], v[192:195], v[124:127]
	v_mfma_f32_16x16x32_bf16 v[120:123], v[156:159], v[192:195], v[120:123]
	v_mfma_f32_16x16x32_bf16 v[108:111], v[148:151], v[204:207], v[108:111]
	v_mfma_f32_16x16x32_bf16 v[104:107], v[156:159], v[204:207], v[104:107]
	v_mfma_f32_16x16x32_bf16 v[92:95], v[148:151], v[212:215], v[92:95]
	v_mfma_f32_16x16x32_bf16 v[88:91], v[156:159], v[212:215], v[88:91]
	v_mfma_f32_16x16x32_bf16 v[76:79], v[148:151], v[220:223], v[76:79]
	v_mfma_f32_16x16x32_bf16 v[72:75], v[156:159], v[220:223], v[72:75]
	v_mfma_f32_16x16x32_bf16 v[124:127], v[152:155], v[196:199], v[124:127]
	v_mfma_f32_16x16x32_bf16 v[120:123], v[160:163], v[196:199], v[120:123]
	v_mfma_f32_16x16x32_bf16 v[108:111], v[152:155], v[208:211], v[108:111]
	v_mfma_f32_16x16x32_bf16 v[104:107], v[160:163], v[208:211], v[104:107]
	v_mfma_f32_16x16x32_bf16 v[92:95], v[152:155], v[216:219], v[92:95]
	v_mfma_f32_16x16x32_bf16 v[88:91], v[160:163], v[216:219], v[88:91]
	v_mfma_f32_16x16x32_bf16 v[76:79], v[152:155], v[224:227], v[76:79]
	v_mfma_f32_16x16x32_bf16 v[72:75], v[160:163], v[224:227], v[72:75]
	s_setprio 0
	s_setprio 1
	v_mfma_f32_16x16x32_bf16 v[116:119], v[164:167], v[192:195], v[116:119]
	v_mfma_f32_16x16x32_bf16 v[112:115], v[184:187], v[192:195], v[112:115]
	v_mfma_f32_16x16x32_bf16 v[100:103], v[164:167], v[204:207], v[100:103]
	v_mfma_f32_16x16x32_bf16 v[96:99], v[184:187], v[204:207], v[96:99]
	v_mfma_f32_16x16x32_bf16 v[84:87], v[164:167], v[212:215], v[84:87]
	v_mfma_f32_16x16x32_bf16 v[80:83], v[184:187], v[212:215], v[80:83]
	v_mfma_f32_16x16x32_bf16 v[68:71], v[164:167], v[220:223], v[68:71]
	v_mfma_f32_16x16x32_bf16 v[64:67], v[184:187], v[220:223], v[64:67]
	v_mfma_f32_16x16x32_bf16 v[116:119], v[180:183], v[196:199], v[116:119]
	v_mfma_f32_16x16x32_bf16 v[112:115], v[188:191], v[196:199], v[112:115]
	v_mfma_f32_16x16x32_bf16 v[100:103], v[180:183], v[208:211], v[100:103]
	v_mfma_f32_16x16x32_bf16 v[96:99], v[188:191], v[208:211], v[96:99]
	v_mfma_f32_16x16x32_bf16 v[84:87], v[180:183], v[216:219], v[84:87]
	v_mfma_f32_16x16x32_bf16 v[80:83], v[188:191], v[216:219], v[80:83]
	v_mfma_f32_16x16x32_bf16 v[68:71], v[180:183], v[224:227], v[68:71]
	v_mfma_f32_16x16x32_bf16 v[64:67], v[188:191], v[224:227], v[64:67]
	s_setprio 0
	s_barrier
	s_add_i32 s67, s63, s31
	v_lshl_add_u64 v[168:169], s[52:53], 0, v[130:131]
	s_mov_b32 m0, s67
	ds_read_b128 v[192:195], v175 offset:16384
	ds_read_b128 v[196:199], v175 offset:17408
	ds_read_b128 v[204:207], v175 offset:18432
	ds_read_b128 v[208:211], v175 offset:19456
	ds_read_b128 v[212:215], v175 offset:20480
	ds_read_b128 v[216:219], v175 offset:21504
	ds_read_b128 v[220:223], v175 offset:22528
	ds_read_b128 v[224:227], v175 offset:23552
	global_load_lds_dwordx4 v130, s[52:53]
	s_add_i32 m0, s67, 0x2000
	s_add_u32 s68, s52, 0x40000
	v_lshl_add_u64 v[200:201], s[52:53], 0, v[134:135]
	s_addc_u32 s69, s53, 0
	s_add_i32 s67, s64, s31
	global_load_lds_dwordx4 v134, s[52:53]
	s_mov_b32 m0, s67
	v_lshl_add_u64 v[230:231], s[54:55], 0, v[132:133]
	global_load_lds_dwordx4 v130, s[68:69]
	s_add_i32 m0, s67, 0x2000
	s_nop 0
	global_load_lds_dwordx4 v134, s[68:69]
	v_lshl_add_u64 v[228:229], s[54:55], 0, v[128:129]
	s_mov_b32 m0, s35
	s_nop 0
	global_load_lds_dwordx4 v128, s[54:55]
	s_mov_b32 m0, s37
	s_nop 0
	global_load_lds_dwordx4 v132, s[54:55]
	s_waitcnt vmcnt(8)
	s_waitcnt lgkmcnt(0)
	s_barrier
	s_setprio 1
	s_waitcnt lgkmcnt(0)
	v_mfma_f32_16x16x32_bf16 v[60:63], v[148:151], v[192:195], v[60:63]
	v_mfma_f32_16x16x32_bf16 v[56:59], v[156:159], v[192:195], v[56:59]
	v_mfma_f32_16x16x32_bf16 v[44:47], v[148:151], v[204:207], v[44:47]
	v_mfma_f32_16x16x32_bf16 v[40:43], v[156:159], v[204:207], v[40:43]
	v_mfma_f32_16x16x32_bf16 v[28:31], v[148:151], v[212:215], v[28:31]
	v_mfma_f32_16x16x32_bf16 v[24:27], v[156:159], v[212:215], v[24:27]
	v_mfma_f32_16x16x32_bf16 v[12:15], v[148:151], v[220:223], v[12:15]
	v_mfma_f32_16x16x32_bf16 v[8:11], v[156:159], v[220:223], v[8:11]
	v_mfma_f32_16x16x32_bf16 v[60:63], v[152:155], v[196:199], v[60:63]
	v_mfma_f32_16x16x32_bf16 v[56:59], v[160:163], v[196:199], v[56:59]
	v_mfma_f32_16x16x32_bf16 v[44:47], v[152:155], v[208:211], v[44:47]
	v_mfma_f32_16x16x32_bf16 v[40:43], v[160:163], v[208:211], v[40:43]
	v_mfma_f32_16x16x32_bf16 v[28:31], v[152:155], v[216:219], v[28:31]
	v_mfma_f32_16x16x32_bf16 v[24:27], v[160:163], v[216:219], v[24:27]
	v_mfma_f32_16x16x32_bf16 v[12:15], v[152:155], v[224:227], v[12:15]
	v_mfma_f32_16x16x32_bf16 v[8:11], v[160:163], v[224:227], v[8:11]
	s_setprio 0
	s_setprio 1
	v_mfma_f32_16x16x32_bf16 v[52:55], v[164:167], v[192:195], v[52:55]
	v_mfma_f32_16x16x32_bf16 v[48:51], v[184:187], v[192:195], v[48:51]
	v_mfma_f32_16x16x32_bf16 v[36:39], v[164:167], v[204:207], v[36:39]
	v_mfma_f32_16x16x32_bf16 v[32:35], v[184:187], v[204:207], v[32:35]
	v_mfma_f32_16x16x32_bf16 v[20:23], v[164:167], v[212:215], v[20:23]
	v_mfma_f32_16x16x32_bf16 v[16:19], v[184:187], v[212:215], v[16:19]
	v_mfma_f32_16x16x32_bf16 v[4:7], v[164:167], v[220:223], v[4:7]
	v_mfma_f32_16x16x32_bf16 v[0:3], v[184:187], v[220:223], v[0:3]
	v_mfma_f32_16x16x32_bf16 v[52:55], v[180:183], v[196:199], v[52:55]
	v_mfma_f32_16x16x32_bf16 v[48:51], v[188:191], v[196:199], v[48:51]
	v_mfma_f32_16x16x32_bf16 v[36:39], v[180:183], v[208:211], v[36:39]
	v_mfma_f32_16x16x32_bf16 v[32:35], v[188:191], v[208:211], v[32:35]
	v_mfma_f32_16x16x32_bf16 v[20:23], v[180:183], v[216:219], v[20:23]
	v_mfma_f32_16x16x32_bf16 v[16:19], v[188:191], v[216:219], v[16:19]
	v_mfma_f32_16x16x32_bf16 v[4:7], v[180:183], v[224:227], v[4:7]
	v_mfma_f32_16x16x32_bf16 v[0:3], v[188:191], v[224:227], v[0:3]
	s_setprio 0
	s_barrier
	s_add_i32 s67, 0, 0x18000
	v_add_u32_e32 v137, s67, v171
	s_add_i32 s68, 0, 0x1c000
	ds_read_b128 v[148:151], v137
	ds_read_b128 v[152:155], v137 offset:1024
	ds_read_b128 v[156:159], v137 offset:2048
	ds_read_b128 v[160:163], v137 offset:3072
	v_add_u32_e32 v137, s68, v171
	ds_read_b128 v[164:167], v137
	ds_read_b128 v[180:183], v137 offset:1024
	ds_read_b128 v[184:187], v137 offset:2048
	ds_read_b128 v[188:191], v137 offset:3072
	s_add_u32 s54, s54, 0x40000
	s_addc_u32 s55, s55, 0
	s_mov_b32 m0, s39
	ds_read_b128 v[192:195], v175 offset:32768
	ds_read_b128 v[196:199], v175 offset:33792
	ds_read_b128 v[204:207], v175 offset:34816
	ds_read_b128 v[208:211], v175 offset:35840
	ds_read_b128 v[212:215], v175 offset:36864
	ds_read_b128 v[216:219], v175 offset:37888
	ds_read_b128 v[220:223], v175 offset:38912
	ds_read_b128 v[224:227], v175 offset:39936
	global_load_lds_dwordx4 v128, s[54:55]
	s_mov_b32 m0, s41
	s_nop 0
	global_load_lds_dwordx4 v132, s[54:55]
	s_waitcnt vmcnt(8)
	s_waitcnt lgkmcnt(0)
	s_barrier
	s_setprio 1
	s_waitcnt lgkmcnt(0)
	v_mfma_f32_16x16x32_bf16 v[124:127], v[148:151], v[192:195], v[124:127]
	v_mfma_f32_16x16x32_bf16 v[120:123], v[156:159], v[192:195], v[120:123]
	v_mfma_f32_16x16x32_bf16 v[108:111], v[148:151], v[204:207], v[108:111]
	v_mfma_f32_16x16x32_bf16 v[104:107], v[156:159], v[204:207], v[104:107]
	v_mfma_f32_16x16x32_bf16 v[92:95], v[148:151], v[212:215], v[92:95]
	v_mfma_f32_16x16x32_bf16 v[88:91], v[156:159], v[212:215], v[88:91]
	v_mfma_f32_16x16x32_bf16 v[76:79], v[148:151], v[220:223], v[76:79]
	v_mfma_f32_16x16x32_bf16 v[72:75], v[156:159], v[220:223], v[72:75]
	v_mfma_f32_16x16x32_bf16 v[124:127], v[152:155], v[196:199], v[124:127]
	v_mfma_f32_16x16x32_bf16 v[120:123], v[160:163], v[196:199], v[120:123]
	v_mfma_f32_16x16x32_bf16 v[108:111], v[152:155], v[208:211], v[108:111]
	v_mfma_f32_16x16x32_bf16 v[104:107], v[160:163], v[208:211], v[104:107]
	v_mfma_f32_16x16x32_bf16 v[92:95], v[152:155], v[216:219], v[92:95]
	v_mfma_f32_16x16x32_bf16 v[88:91], v[160:163], v[216:219], v[88:91]
	v_mfma_f32_16x16x32_bf16 v[76:79], v[152:155], v[224:227], v[76:79]
	v_mfma_f32_16x16x32_bf16 v[72:75], v[160:163], v[224:227], v[72:75]
	s_setprio 0
	s_setprio 1
	v_mfma_f32_16x16x32_bf16 v[116:119], v[164:167], v[192:195], v[116:119]
	v_mfma_f32_16x16x32_bf16 v[112:115], v[184:187], v[192:195], v[112:115]
	v_mfma_f32_16x16x32_bf16 v[100:103], v[164:167], v[204:207], v[100:103]
	v_mfma_f32_16x16x32_bf16 v[96:99], v[184:187], v[204:207], v[96:99]
	v_mfma_f32_16x16x32_bf16 v[84:87], v[164:167], v[212:215], v[84:87]
	v_mfma_f32_16x16x32_bf16 v[80:83], v[184:187], v[212:215], v[80:83]
	v_mfma_f32_16x16x32_bf16 v[68:71], v[164:167], v[220:223], v[68:71]
	v_mfma_f32_16x16x32_bf16 v[64:67], v[184:187], v[220:223], v[64:67]
	v_mfma_f32_16x16x32_bf16 v[116:119], v[180:183], v[196:199], v[116:119]
	v_mfma_f32_16x16x32_bf16 v[112:115], v[188:191], v[196:199], v[112:115]
	v_mfma_f32_16x16x32_bf16 v[100:103], v[180:183], v[208:211], v[100:103]
	v_mfma_f32_16x16x32_bf16 v[96:99], v[188:191], v[208:211], v[96:99]
	v_mfma_f32_16x16x32_bf16 v[84:87], v[180:183], v[216:219], v[84:87]
	v_mfma_f32_16x16x32_bf16 v[80:83], v[188:191], v[216:219], v[80:83]
	v_mfma_f32_16x16x32_bf16 v[68:71], v[180:183], v[224:227], v[68:71]
	v_mfma_f32_16x16x32_bf16 v[64:67], v[188:191], v[224:227], v[64:67]
	s_setprio 0
	s_barrier
	s_add_i32 s54, s67, s31
	v_lshl_add_u64 v[168:169], v[168:169], 0, s[22:23]
	s_mov_b32 m0, s54
	ds_read_b128 v[192:195], v175 offset:49152
	ds_read_b128 v[196:199], v175 offset:50176
	ds_read_b128 v[204:207], v175 offset:51200
	ds_read_b128 v[208:211], v175 offset:52224
	ds_read_b128 v[212:215], v175 offset:53248
	ds_read_b128 v[216:219], v175 offset:54272
	ds_read_b128 v[220:223], v175 offset:55296
	ds_read_b128 v[224:227], v175 offset:56320
	global_load_lds_dwordx4 v[168:169], off
	s_add_i32 m0, s54, 0x2000
	s_add_u32 s52, s52, 0x40080
	v_lshl_add_u64 v[168:169], v[200:201], 0, s[22:23]
	s_addc_u32 s53, s53, 0
	s_add_i32 s54, s68, s31
	global_load_lds_dwordx4 v[168:169], off
	s_mov_b32 m0, s54
	s_nop 0
	global_load_lds_dwordx4 v130, s[52:53]
	s_add_i32 m0, s54, 0x2000
	s_nop 0
	global_load_lds_dwordx4 v134, s[52:53]
	v_lshl_add_u64 v[168:169], v[228:229], 0, s[22:23]
	s_mov_b32 m0, s60
	s_nop 0
	global_load_lds_dwordx4 v[168:169], off
	v_lshl_add_u64 v[168:169], v[230:231], 0, s[22:23]
	s_mov_b32 m0, s61
	s_nop 0
	global_load_lds_dwordx4 v[168:169], off
	s_waitcnt vmcnt(8)
	s_waitcnt lgkmcnt(0)
	s_barrier
	s_setprio 1
	s_waitcnt lgkmcnt(0)
	v_mfma_f32_16x16x32_bf16 v[60:63], v[148:151], v[192:195], v[60:63]
	v_mfma_f32_16x16x32_bf16 v[56:59], v[156:159], v[192:195], v[56:59]
	v_mfma_f32_16x16x32_bf16 v[44:47], v[148:151], v[204:207], v[44:47]
	v_mfma_f32_16x16x32_bf16 v[40:43], v[156:159], v[204:207], v[40:43]
	v_mfma_f32_16x16x32_bf16 v[28:31], v[148:151], v[212:215], v[28:31]
	v_mfma_f32_16x16x32_bf16 v[24:27], v[156:159], v[212:215], v[24:27]
	v_mfma_f32_16x16x32_bf16 v[12:15], v[148:151], v[220:223], v[12:15]
	v_mfma_f32_16x16x32_bf16 v[8:11], v[156:159], v[220:223], v[8:11]
	v_mfma_f32_16x16x32_bf16 v[60:63], v[152:155], v[196:199], v[60:63]
	v_mfma_f32_16x16x32_bf16 v[56:59], v[160:163], v[196:199], v[56:59]
	v_mfma_f32_16x16x32_bf16 v[44:47], v[152:155], v[208:211], v[44:47]
	v_mfma_f32_16x16x32_bf16 v[40:43], v[160:163], v[208:211], v[40:43]
	v_mfma_f32_16x16x32_bf16 v[28:31], v[152:155], v[216:219], v[28:31]
	v_mfma_f32_16x16x32_bf16 v[24:27], v[160:163], v[216:219], v[24:27]
	v_mfma_f32_16x16x32_bf16 v[12:15], v[152:155], v[224:227], v[12:15]
	v_mfma_f32_16x16x32_bf16 v[8:11], v[160:163], v[224:227], v[8:11]
	s_setprio 0
	s_setprio 1
	v_mfma_f32_16x16x32_bf16 v[52:55], v[164:167], v[192:195], v[52:55]
	v_mfma_f32_16x16x32_bf16 v[48:51], v[184:187], v[192:195], v[48:51]
	v_mfma_f32_16x16x32_bf16 v[36:39], v[164:167], v[204:207], v[36:39]
	v_mfma_f32_16x16x32_bf16 v[32:35], v[184:187], v[204:207], v[32:35]
	v_mfma_f32_16x16x32_bf16 v[20:23], v[164:167], v[212:215], v[20:23]
	v_mfma_f32_16x16x32_bf16 v[16:19], v[184:187], v[212:215], v[16:19]
	v_mfma_f32_16x16x32_bf16 v[4:7], v[164:167], v[220:223], v[4:7]
	v_mfma_f32_16x16x32_bf16 v[0:3], v[184:187], v[220:223], v[0:3]
	v_mfma_f32_16x16x32_bf16 v[52:55], v[180:183], v[196:199], v[52:55]
	v_mfma_f32_16x16x32_bf16 v[48:51], v[188:191], v[196:199], v[48:51]
	v_mfma_f32_16x16x32_bf16 v[36:39], v[180:183], v[208:211], v[36:39]
	v_mfma_f32_16x16x32_bf16 v[32:35], v[188:191], v[208:211], v[32:35]
	v_mfma_f32_16x16x32_bf16 v[20:23], v[180:183], v[216:219], v[20:23]
	v_mfma_f32_16x16x32_bf16 v[16:19], v[188:191], v[216:219], v[16:19]
	v_mfma_f32_16x16x32_bf16 v[4:7], v[180:183], v[224:227], v[4:7]
	v_mfma_f32_16x16x32_bf16 v[0:3], v[188:191], v[224:227], v[0:3]
	s_setprio 0
	s_barrier
	s_add_i32 s66, s66, 2
	s_add_u32 s50, s50, 0x100
	s_addc_u32 s51, s51, 0
	s_add_u32 s43, s43, 0x100
	s_addc_u32 s45, s45, 0
	s_cmp_gt_u32 s66, 13
	s_cbranch_scc0 .LBB0_220
	s_and_b64 vcc, exec, s[24:25]
	s_cbranch_vccz .LBB0_223
	s_barrier

.LBB0_401:
	ds_read_b128 v[128:131], v189
	ds_read_b128 v[132:135], v189 offset:1024
	ds_read_b128 v[136:139], v189 offset:2048
	ds_read_b128 v[140:143], v189 offset:3072
	ds_read_b128 v[144:147], v190
	ds_read_b128 v[148:151], v190 offset:1024
	ds_read_b128 v[168:171], v190 offset:2048
	ds_read_b128 v[172:175], v190 offset:3072
	s_add_u32 s4, s42, 0xfff80080
	s_addc_u32 s5, s43, -1
	s_cmp_eq_u32 s59, 28
	s_cselect_b32 s45, s35, s5
	s_cselect_b32 s44, s41, s4
	s_cselect_b32 s5, s31, s58
	s_cselect_b32 s4, s56, s57
	s_add_i32 m0, s47, 0xc000
	ds_read_b128 v[176:179], v191
	ds_read_b128 v[180:183], v191 offset:1024
	ds_read_b128 v[194:197], v191 offset:2048
	ds_read_b128 v[198:201], v191 offset:3072
	ds_read_b128 v[204:207], v191 offset:4096
	ds_read_b128 v[208:211], v191 offset:5120
	ds_read_b128 v[212:215], v191 offset:6144
	ds_read_b128 v[216:219], v191 offset:7168
	global_load_lds_dwordx4 v160, s[42:43]
	s_add_i32 m0, s47, 0xe000
	s_nop 0
	global_load_lds_dwordx4 v162, s[42:43]
	s_waitcnt vmcnt(8)
	s_waitcnt lgkmcnt(0)
	s_barrier
	s_setprio 1
	s_waitcnt lgkmcnt(0)
	v_mfma_f32_16x16x32_bf16 v[124:127], v[128:131], v[176:179], v[124:127]
	v_mfma_f32_16x16x32_bf16 v[120:123], v[136:139], v[176:179], v[120:123]
	v_mfma_f32_16x16x32_bf16 v[108:111], v[128:131], v[194:197], v[108:111]
	v_mfma_f32_16x16x32_bf16 v[104:107], v[136:139], v[194:197], v[104:107]
	v_mfma_f32_16x16x32_bf16 v[92:95], v[128:131], v[204:207], v[92:95]
	v_mfma_f32_16x16x32_bf16 v[88:91], v[136:139], v[204:207], v[88:91]
	v_mfma_f32_16x16x32_bf16 v[76:79], v[128:131], v[212:215], v[76:79]
	v_mfma_f32_16x16x32_bf16 v[72:75], v[136:139], v[212:215], v[72:75]
	v_mfma_f32_16x16x32_bf16 v[124:127], v[132:135], v[180:183], v[124:127]
	v_mfma_f32_16x16x32_bf16 v[120:123], v[140:143], v[180:183], v[120:123]
	v_mfma_f32_16x16x32_bf16 v[108:111], v[132:135], v[198:201], v[108:111]
	v_mfma_f32_16x16x32_bf16 v[104:107], v[140:143], v[198:201], v[104:107]
	v_mfma_f32_16x16x32_bf16 v[92:95], v[132:135], v[208:211], v[92:95]
	v_mfma_f32_16x16x32_bf16 v[88:91], v[140:143], v[208:211], v[88:91]
	v_mfma_f32_16x16x32_bf16 v[76:79], v[132:135], v[216:219], v[76:79]
	v_mfma_f32_16x16x32_bf16 v[72:75], v[140:143], v[216:219], v[72:75]
	s_setprio 0
	s_setprio 1
	v_mfma_f32_16x16x32_bf16 v[116:119], v[144:147], v[176:179], v[116:119]
	v_mfma_f32_16x16x32_bf16 v[112:115], v[168:171], v[176:179], v[112:115]
	v_mfma_f32_16x16x32_bf16 v[100:103], v[144:147], v[194:197], v[100:103]
	v_mfma_f32_16x16x32_bf16 v[96:99], v[168:171], v[194:197], v[96:99]
	v_mfma_f32_16x16x32_bf16 v[84:87], v[144:147], v[204:207], v[84:87]
	v_mfma_f32_16x16x32_bf16 v[80:83], v[168:171], v[204:207], v[80:83]
	v_mfma_f32_16x16x32_bf16 v[68:71], v[144:147], v[212:215], v[68:71]
	v_mfma_f32_16x16x32_bf16 v[64:67], v[168:171], v[212:215], v[64:67]
	v_mfma_f32_16x16x32_bf16 v[116:119], v[148:151], v[180:183], v[116:119]
	v_mfma_f32_16x16x32_bf16 v[112:115], v[172:175], v[180:183], v[112:115]
	v_mfma_f32_16x16x32_bf16 v[100:103], v[148:151], v[198:201], v[100:103]
	v_mfma_f32_16x16x32_bf16 v[96:99], v[172:175], v[198:201], v[96:99]
	v_mfma_f32_16x16x32_bf16 v[84:87], v[148:151], v[208:211], v[84:87]
	v_mfma_f32_16x16x32_bf16 v[80:83], v[172:175], v[208:211], v[80:83]
	v_mfma_f32_16x16x32_bf16 v[68:71], v[148:151], v[216:219], v[68:71]
	v_mfma_f32_16x16x32_bf16 v[64:67], v[172:175], v[216:219], v[64:67]
	s_setprio 0
	s_barrier
	s_add_i32 s60, s53, s46
	v_lshl_add_u64 v[184:185], s[4:5], 0, v[154:155]
	s_mov_b32 m0, s60
	ds_read_b128 v[176:179], v191 offset:16384
	ds_read_b128 v[180:183], v191 offset:17408
	ds_read_b128 v[194:197], v191 offset:18432
	ds_read_b128 v[198:201], v191 offset:19456
	ds_read_b128 v[204:207], v191 offset:20480
	ds_read_b128 v[208:211], v191 offset:21504
	ds_read_b128 v[212:215], v191 offset:22528
	ds_read_b128 v[216:219], v191 offset:23552
	global_load_lds_dwordx4 v154, s[4:5]
	s_add_i32 m0, s60, 0x2000
	s_add_u32 s60, s4, 0x80000
	v_lshl_add_u64 v[220:221], s[4:5], 0, v[158:159]
	s_addc_u32 s61, s5, 0
	s_add_i32 s62, s54, s46
	global_load_lds_dwordx4 v158, s[4:5]
	s_mov_b32 m0, s62
	v_lshl_add_u64 v[224:225], s[44:45], 0, v[156:157]
	global_load_lds_dwordx4 v154, s[60:61]
	s_add_i32 m0, s62, 0x2000
	s_nop 0
	global_load_lds_dwordx4 v158, s[60:61]
	v_lshl_add_u64 v[222:223], s[44:45], 0, v[152:153]
	s_mov_b32 m0, s47
	s_nop 0
	global_load_lds_dwordx4 v152, s[44:45]
	s_mov_b32 m0, s48
	s_nop 0
	global_load_lds_dwordx4 v156, s[44:45]
	s_waitcnt vmcnt(8)
	s_waitcnt lgkmcnt(0)
	s_barrier
	s_setprio 1
	s_waitcnt lgkmcnt(0)
	v_mfma_f32_16x16x32_bf16 v[60:63], v[128:131], v[176:179], v[60:63]
	v_mfma_f32_16x16x32_bf16 v[56:59], v[136:139], v[176:179], v[56:59]
	v_mfma_f32_16x16x32_bf16 v[44:47], v[128:131], v[194:197], v[44:47]
	v_mfma_f32_16x16x32_bf16 v[40:43], v[136:139], v[194:197], v[40:43]
	v_mfma_f32_16x16x32_bf16 v[28:31], v[128:131], v[204:207], v[28:31]
	v_mfma_f32_16x16x32_bf16 v[24:27], v[136:139], v[204:207], v[24:27]
	v_mfma_f32_16x16x32_bf16 v[12:15], v[128:131], v[212:215], v[12:15]
	v_mfma_f32_16x16x32_bf16 v[8:11], v[136:139], v[212:215], v[8:11]
	v_mfma_f32_16x16x32_bf16 v[60:63], v[132:135], v[180:183], v[60:63]
	v_mfma_f32_16x16x32_bf16 v[56:59], v[140:143], v[180:183], v[56:59]
	v_mfma_f32_16x16x32_bf16 v[44:47], v[132:135], v[198:201], v[44:47]
	v_mfma_f32_16x16x32_bf16 v[40:43], v[140:143], v[198:201], v[40:43]
	v_mfma_f32_16x16x32_bf16 v[28:31], v[132:135], v[208:211], v[28:31]
	v_mfma_f32_16x16x32_bf16 v[24:27], v[140:143], v[208:211], v[24:27]
	v_mfma_f32_16x16x32_bf16 v[12:15], v[132:135], v[216:219], v[12:15]
	v_mfma_f32_16x16x32_bf16 v[8:11], v[140:143], v[216:219], v[8:11]
	s_setprio 0
	s_setprio 1
	v_mfma_f32_16x16x32_bf16 v[52:55], v[144:147], v[176:179], v[52:55]
	v_mfma_f32_16x16x32_bf16 v[48:51], v[168:171], v[176:179], v[48:51]
	v_mfma_f32_16x16x32_bf16 v[36:39], v[144:147], v[194:197], v[36:39]
	v_mfma_f32_16x16x32_bf16 v[32:35], v[168:171], v[194:197], v[32:35]
	v_mfma_f32_16x16x32_bf16 v[20:23], v[144:147], v[204:207], v[20:23]
	v_mfma_f32_16x16x32_bf16 v[16:19], v[168:171], v[204:207], v[16:19]
	v_mfma_f32_16x16x32_bf16 v[4:7], v[144:147], v[212:215], v[4:7]
	v_mfma_f32_16x16x32_bf16 v[0:3], v[168:171], v[212:215], v[0:3]
	v_mfma_f32_16x16x32_bf16 v[52:55], v[148:151], v[180:183], v[52:55]
	v_mfma_f32_16x16x32_bf16 v[48:51], v[172:175], v[180:183], v[48:51]
	v_mfma_f32_16x16x32_bf16 v[36:39], v[148:151], v[198:201], v[36:39]
	v_mfma_f32_16x16x32_bf16 v[32:35], v[172:175], v[198:201], v[32:35]
	v_mfma_f32_16x16x32_bf16 v[20:23], v[148:151], v[208:211], v[20:23]
	v_mfma_f32_16x16x32_bf16 v[16:19], v[172:175], v[208:211], v[16:19]
	v_mfma_f32_16x16x32_bf16 v[4:7], v[148:151], v[216:219], v[4:7]
	v_mfma_f32_16x16x32_bf16 v[0:3], v[172:175], v[216:219], v[0:3]
	s_setprio 0
	s_barrier
	s_add_i32 s60, 0, 0x18000
	s_add_i32 s61, 0, 0x1c000
	v_add_u32_e32 v140, s60, v187
	v_add_u32_e32 v172, s61, v187
	ds_read_b128 v[128:131], v140
	ds_read_b128 v[132:135], v140 offset:1024
	ds_read_b128 v[136:139], v140 offset:2048
	ds_read_b128 v[140:143], v140 offset:3072
	ds_read_b128 v[144:147], v172
	ds_read_b128 v[148:151], v172 offset:1024
	ds_read_b128 v[168:171], v172 offset:2048
	ds_read_b128 v[172:175], v172 offset:3072
	s_add_u32 s44, s44, 0x80000
	s_addc_u32 s45, s45, 0
	s_mov_b32 m0, s49
	ds_read_b128 v[176:179], v191 offset:32768
	ds_read_b128 v[180:183], v191 offset:33792
	ds_read_b128 v[194:197], v191 offset:34816
	ds_read_b128 v[198:201], v191 offset:35840
	ds_read_b128 v[204:207], v191 offset:36864
	ds_read_b128 v[208:211], v191 offset:37888
	ds_read_b128 v[212:215], v191 offset:38912
	ds_read_b128 v[216:219], v191 offset:39936
	global_load_lds_dwordx4 v152, s[44:45]
	s_mov_b32 m0, s50
	s_nop 0
	global_load_lds_dwordx4 v156, s[44:45]
	s_waitcnt vmcnt(8)
	s_waitcnt lgkmcnt(0)
	s_barrier
	s_setprio 1
	s_waitcnt lgkmcnt(0)
	v_mfma_f32_16x16x32_bf16 v[124:127], v[128:131], v[176:179], v[124:127]
	v_mfma_f32_16x16x32_bf16 v[120:123], v[136:139], v[176:179], v[120:123]
	v_mfma_f32_16x16x32_bf16 v[108:111], v[128:131], v[194:197], v[108:111]
	v_mfma_f32_16x16x32_bf16 v[104:107], v[136:139], v[194:197], v[104:107]
	v_mfma_f32_16x16x32_bf16 v[92:95], v[128:131], v[204:207], v[92:95]
	v_mfma_f32_16x16x32_bf16 v[88:91], v[136:139], v[204:207], v[88:91]
	v_mfma_f32_16x16x32_bf16 v[76:79], v[128:131], v[212:215], v[76:79]
	v_mfma_f32_16x16x32_bf16 v[72:75], v[136:139], v[212:215], v[72:75]
	v_mfma_f32_16x16x32_bf16 v[124:127], v[132:135], v[180:183], v[124:127]
	v_mfma_f32_16x16x32_bf16 v[120:123], v[140:143], v[180:183], v[120:123]
	v_mfma_f32_16x16x32_bf16 v[108:111], v[132:135], v[198:201], v[108:111]
	v_mfma_f32_16x16x32_bf16 v[104:107], v[140:143], v[198:201], v[104:107]
	v_mfma_f32_16x16x32_bf16 v[92:95], v[132:135], v[208:211], v[92:95]
	v_mfma_f32_16x16x32_bf16 v[88:91], v[140:143], v[208:211], v[88:91]
	v_mfma_f32_16x16x32_bf16 v[76:79], v[132:135], v[216:219], v[76:79]
	v_mfma_f32_16x16x32_bf16 v[72:75], v[140:143], v[216:219], v[72:75]
	s_setprio 0
	s_setprio 1
	v_mfma_f32_16x16x32_bf16 v[116:119], v[144:147], v[176:179], v[116:119]
	v_mfma_f32_16x16x32_bf16 v[112:115], v[168:171], v[176:179], v[112:115]
	v_mfma_f32_16x16x32_bf16 v[100:103], v[144:147], v[194:197], v[100:103]
	v_mfma_f32_16x16x32_bf16 v[96:99], v[168:171], v[194:197], v[96:99]
	v_mfma_f32_16x16x32_bf16 v[84:87], v[144:147], v[204:207], v[84:87]
	v_mfma_f32_16x16x32_bf16 v[80:83], v[168:171], v[204:207], v[80:83]
	v_mfma_f32_16x16x32_bf16 v[68:71], v[144:147], v[212:215], v[68:71]
	v_mfma_f32_16x16x32_bf16 v[64:67], v[168:171], v[212:215], v[64:67]
	v_mfma_f32_16x16x32_bf16 v[116:119], v[148:151], v[180:183], v[116:119]
	v_mfma_f32_16x16x32_bf16 v[112:115], v[172:175], v[180:183], v[112:115]
	v_mfma_f32_16x16x32_bf16 v[100:103], v[148:151], v[198:201], v[100:103]
	v_mfma_f32_16x16x32_bf16 v[96:99], v[172:175], v[198:201], v[96:99]
	v_mfma_f32_16x16x32_bf16 v[84:87], v[148:151], v[208:211], v[84:87]
	v_mfma_f32_16x16x32_bf16 v[80:83], v[172:175], v[208:211], v[80:83]
	v_mfma_f32_16x16x32_bf16 v[68:71], v[148:151], v[216:219], v[68:71]
	v_mfma_f32_16x16x32_bf16 v[64:67], v[172:175], v[216:219], v[64:67]
	s_setprio 0
	s_barrier
	s_add_i32 s44, s60, s46
	v_lshl_add_u64 v[184:185], v[184:185], 0, s[26:27]
	s_mov_b32 m0, s44
	ds_read_b128 v[176:179], v191 offset:49152
	ds_read_b128 v[180:183], v191 offset:50176
	ds_read_b128 v[194:197], v191 offset:51200
	ds_read_b128 v[198:201], v191 offset:52224
	ds_read_b128 v[204:207], v191 offset:53248
	ds_read_b128 v[208:211], v191 offset:54272
	ds_read_b128 v[212:215], v191 offset:55296
	ds_read_b128 v[216:219], v191 offset:56320
	global_load_lds_dwordx4 v[184:185], off
	s_add_i32 m0, s44, 0x2000
	s_add_u32 s4, s4, 0x80080
	v_lshl_add_u64 v[184:185], v[220:221], 0, s[26:27]
	s_addc_u32 s5, s5, 0
	s_add_i32 s44, s61, s46
	global_load_lds_dwordx4 v[184:185], off
	s_mov_b32 m0, s44
	s_nop 0
	global_load_lds_dwordx4 v154, s[4:5]
	s_add_i32 m0, s44, 0x2000
	s_nop 0
	global_load_lds_dwordx4 v158, s[4:5]
	v_lshl_add_u64 v[184:185], v[222:223], 0, s[26:27]
	s_mov_b32 m0, s33
	s_nop 0
	global_load_lds_dwordx4 v[184:185], off
	v_lshl_add_u64 v[184:185], v[224:225], 0, s[26:27]
	s_mov_b32 m0, s52
	s_nop 0
	global_load_lds_dwordx4 v[184:185], off
	s_waitcnt vmcnt(8)
	s_waitcnt lgkmcnt(0)
	s_barrier
	s_setprio 1
	s_waitcnt lgkmcnt(0)
	v_mfma_f32_16x16x32_bf16 v[60:63], v[128:131], v[176:179], v[60:63]
	v_mfma_f32_16x16x32_bf16 v[56:59], v[136:139], v[176:179], v[56:59]
	v_mfma_f32_16x16x32_bf16 v[44:47], v[128:131], v[194:197], v[44:47]
	v_mfma_f32_16x16x32_bf16 v[40:43], v[136:139], v[194:197], v[40:43]
	v_mfma_f32_16x16x32_bf16 v[28:31], v[128:131], v[204:207], v[28:31]
	v_mfma_f32_16x16x32_bf16 v[24:27], v[136:139], v[204:207], v[24:27]
	v_mfma_f32_16x16x32_bf16 v[12:15], v[128:131], v[212:215], v[12:15]
	v_mfma_f32_16x16x32_bf16 v[8:11], v[136:139], v[212:215], v[8:11]
	v_mfma_f32_16x16x32_bf16 v[60:63], v[132:135], v[180:183], v[60:63]
	v_mfma_f32_16x16x32_bf16 v[56:59], v[140:143], v[180:183], v[56:59]
	v_mfma_f32_16x16x32_bf16 v[44:47], v[132:135], v[198:201], v[44:47]
	v_mfma_f32_16x16x32_bf16 v[40:43], v[140:143], v[198:201], v[40:43]
	v_mfma_f32_16x16x32_bf16 v[28:31], v[132:135], v[208:211], v[28:31]
	v_mfma_f32_16x16x32_bf16 v[24:27], v[140:143], v[208:211], v[24:27]
	v_mfma_f32_16x16x32_bf16 v[12:15], v[132:135], v[216:219], v[12:15]
	v_mfma_f32_16x16x32_bf16 v[8:11], v[140:143], v[216:219], v[8:11]
	s_setprio 0
	s_setprio 1
	v_mfma_f32_16x16x32_bf16 v[52:55], v[144:147], v[176:179], v[52:55]
	v_mfma_f32_16x16x32_bf16 v[48:51], v[168:171], v[176:179], v[48:51]
	v_mfma_f32_16x16x32_bf16 v[36:39], v[144:147], v[194:197], v[36:39]
	v_mfma_f32_16x16x32_bf16 v[32:35], v[168:171], v[194:197], v[32:35]
	v_mfma_f32_16x16x32_bf16 v[20:23], v[144:147], v[204:207], v[20:23]
	v_mfma_f32_16x16x32_bf16 v[16:19], v[168:171], v[204:207], v[16:19]
	v_mfma_f32_16x16x32_bf16 v[4:7], v[144:147], v[212:215], v[4:7]
	v_mfma_f32_16x16x32_bf16 v[0:3], v[168:171], v[212:215], v[0:3]
	v_mfma_f32_16x16x32_bf16 v[52:55], v[148:151], v[180:183], v[52:55]
	v_mfma_f32_16x16x32_bf16 v[48:51], v[172:175], v[180:183], v[48:51]
	v_mfma_f32_16x16x32_bf16 v[36:39], v[148:151], v[198:201], v[36:39]
	v_mfma_f32_16x16x32_bf16 v[32:35], v[172:175], v[198:201], v[32:35]
	v_mfma_f32_16x16x32_bf16 v[20:23], v[148:151], v[208:211], v[20:23]
	v_mfma_f32_16x16x32_bf16 v[16:19], v[172:175], v[208:211], v[16:19]
	v_mfma_f32_16x16x32_bf16 v[4:7], v[148:151], v[216:219], v[4:7]
	v_mfma_f32_16x16x32_bf16 v[0:3], v[172:175], v[216:219], v[0:3]
	s_setprio 0
	s_barrier
	s_add_i32 s59, s59, 2
	s_add_u32 s42, s42, 0x100
	s_addc_u32 s43, s43, 0
	s_add_u32 s57, s57, 0x100
	s_addc_u32 s58, s58, 0
	s_cmp_gt_u32 s59, 29
	s_cbranch_scc0 .LBB0_401
	s_and_b64 vcc, exec, s[28:29]
	s_cbranch_vccz .LBB0_404
	s_barrier

.LBB0_483:
	ds_read_b128 v[146:149], v169
	ds_read_b128 v[150:153], v169 offset:1024
	ds_read_b128 v[154:157], v169 offset:2048
	ds_read_b128 v[160:163], v169 offset:3072
	ds_read_b128 v[180:183], v171
	ds_read_b128 v[184:187], v171 offset:1024
	ds_read_b128 v[188:191], v171 offset:2048
	ds_read_b128 v[192:195], v171 offset:3072
	s_add_u32 s4, s10, 0xfffc0080
	s_addc_u32 s5, s11, -1
	s_cmp_eq_u32 s56, 12
	s_cselect_b32 s13, s9, s5
	s_cselect_b32 s12, s37, s4
	s_cselect_b32 s5, s35, s55
	s_cselect_b32 s4, s53, s54
	s_add_i32 m0, s42, 0xc000
	ds_read_b128 v[196:199], v173
	ds_read_b128 v[204:207], v173 offset:1024
	ds_read_b128 v[208:211], v173 offset:2048
	ds_read_b128 v[212:215], v173 offset:3072
	ds_read_b128 v[216:219], v173 offset:4096
	ds_read_b128 v[220:223], v173 offset:5120
	ds_read_b128 v[224:227], v173 offset:6144
	ds_read_b128 v[228:231], v173 offset:7168
	global_load_lds_dwordx4 v138, s[10:11]
	s_add_i32 m0, s42, 0xe000
	s_nop 0
	global_load_lds_dwordx4 v140, s[10:11]
	s_waitcnt vmcnt(8)
	s_waitcnt lgkmcnt(0)
	s_barrier
	s_setprio 1
	s_waitcnt lgkmcnt(0)
	v_mfma_f32_16x16x32_bf16 v[124:127], v[146:149], v[196:199], v[124:127]
	v_mfma_f32_16x16x32_bf16 v[116:119], v[154:157], v[196:199], v[116:119]
	v_mfma_f32_16x16x32_bf16 v[108:111], v[146:149], v[208:211], v[108:111]
	v_mfma_f32_16x16x32_bf16 v[100:103], v[154:157], v[208:211], v[100:103]
	v_mfma_f32_16x16x32_bf16 v[92:95], v[146:149], v[216:219], v[92:95]
	v_mfma_f32_16x16x32_bf16 v[84:87], v[154:157], v[216:219], v[84:87]
	v_mfma_f32_16x16x32_bf16 v[76:79], v[146:149], v[224:227], v[76:79]
	v_mfma_f32_16x16x32_bf16 v[68:71], v[154:157], v[224:227], v[68:71]
	v_mfma_f32_16x16x32_bf16 v[124:127], v[150:153], v[204:207], v[124:127]
	v_mfma_f32_16x16x32_bf16 v[116:119], v[160:163], v[204:207], v[116:119]
	v_mfma_f32_16x16x32_bf16 v[108:111], v[150:153], v[212:215], v[108:111]
	v_mfma_f32_16x16x32_bf16 v[100:103], v[160:163], v[212:215], v[100:103]
	v_mfma_f32_16x16x32_bf16 v[92:95], v[150:153], v[220:223], v[92:95]
	v_mfma_f32_16x16x32_bf16 v[84:87], v[160:163], v[220:223], v[84:87]
	v_mfma_f32_16x16x32_bf16 v[76:79], v[150:153], v[228:231], v[76:79]
	v_mfma_f32_16x16x32_bf16 v[68:71], v[160:163], v[228:231], v[68:71]
	s_setprio 0
	s_setprio 1
	v_mfma_f32_16x16x32_bf16 v[120:123], v[180:183], v[196:199], v[120:123]
	v_mfma_f32_16x16x32_bf16 v[112:115], v[188:191], v[196:199], v[112:115]
	v_mfma_f32_16x16x32_bf16 v[104:107], v[180:183], v[208:211], v[104:107]
	v_mfma_f32_16x16x32_bf16 v[96:99], v[188:191], v[208:211], v[96:99]
	v_mfma_f32_16x16x32_bf16 v[88:91], v[180:183], v[216:219], v[88:91]
	v_mfma_f32_16x16x32_bf16 v[80:83], v[188:191], v[216:219], v[80:83]
	v_mfma_f32_16x16x32_bf16 v[72:75], v[180:183], v[224:227], v[72:75]
	v_mfma_f32_16x16x32_bf16 v[64:67], v[188:191], v[224:227], v[64:67]
	v_mfma_f32_16x16x32_bf16 v[120:123], v[184:187], v[204:207], v[120:123]
	v_mfma_f32_16x16x32_bf16 v[112:115], v[192:195], v[204:207], v[112:115]
	v_mfma_f32_16x16x32_bf16 v[104:107], v[184:187], v[212:215], v[104:107]
	v_mfma_f32_16x16x32_bf16 v[96:99], v[192:195], v[212:215], v[96:99]
	v_mfma_f32_16x16x32_bf16 v[88:91], v[184:187], v[220:223], v[88:91]
	v_mfma_f32_16x16x32_bf16 v[80:83], v[192:195], v[220:223], v[80:83]
	v_mfma_f32_16x16x32_bf16 v[72:75], v[184:187], v[228:231], v[72:75]
	v_mfma_f32_16x16x32_bf16 v[64:67], v[192:195], v[228:231], v[64:67]
	s_setprio 0
	s_barrier
	s_add_i32 s57, s49, s23
	v_lshl_add_u64 v[200:201], s[4:5], 0, v[132:133]
	s_mov_b32 m0, s57
	ds_read_b128 v[196:199], v173 offset:16384
	ds_read_b128 v[204:207], v173 offset:17408
	ds_read_b128 v[208:211], v173 offset:18432
	ds_read_b128 v[212:215], v173 offset:19456
	ds_read_b128 v[216:219], v173 offset:20480
	ds_read_b128 v[220:223], v173 offset:21504
	ds_read_b128 v[224:227], v173 offset:22528
	ds_read_b128 v[228:231], v173 offset:23552
	global_load_lds_dwordx4 v132, s[4:5]
	s_add_i32 m0, s57, 0x2000
	s_add_u32 s58, s4, 0x40000
	v_lshl_add_u64 v[232:233], s[4:5], 0, v[128:129]
	s_addc_u32 s59, s5, 0
	s_add_i32 s57, s50, s23
	global_load_lds_dwordx4 v128, s[4:5]
	s_mov_b32 m0, s57
	v_lshl_add_u64 v[236:237], s[12:13], 0, v[130:131]
	global_load_lds_dwordx4 v132, s[58:59]
	s_add_i32 m0, s57, 0x2000
	s_nop 0
	global_load_lds_dwordx4 v128, s[58:59]
	v_lshl_add_u64 v[234:235], s[12:13], 0, v[134:135]
	s_mov_b32 m0, s42
	s_nop 0
	global_load_lds_dwordx4 v134, s[12:13]
	s_mov_b32 m0, s43
	s_nop 0
	global_load_lds_dwordx4 v130, s[12:13]
	s_waitcnt vmcnt(8)
	s_waitcnt lgkmcnt(0)
	s_barrier
	s_setprio 1
	s_waitcnt lgkmcnt(0)
	v_mfma_f32_16x16x32_bf16 v[60:63], v[146:149], v[196:199], v[60:63]
	v_mfma_f32_16x16x32_bf16 v[52:55], v[154:157], v[196:199], v[52:55]
	v_mfma_f32_16x16x32_bf16 v[44:47], v[146:149], v[208:211], v[44:47]
	v_mfma_f32_16x16x32_bf16 v[36:39], v[154:157], v[208:211], v[36:39]
	v_mfma_f32_16x16x32_bf16 v[28:31], v[146:149], v[216:219], v[28:31]
	v_mfma_f32_16x16x32_bf16 v[20:23], v[154:157], v[216:219], v[20:23]
	v_mfma_f32_16x16x32_bf16 v[12:15], v[146:149], v[224:227], v[12:15]
	v_mfma_f32_16x16x32_bf16 v[4:7], v[154:157], v[224:227], v[4:7]
	v_mfma_f32_16x16x32_bf16 v[60:63], v[150:153], v[204:207], v[60:63]
	v_mfma_f32_16x16x32_bf16 v[52:55], v[160:163], v[204:207], v[52:55]
	v_mfma_f32_16x16x32_bf16 v[44:47], v[150:153], v[212:215], v[44:47]
	v_mfma_f32_16x16x32_bf16 v[36:39], v[160:163], v[212:215], v[36:39]
	v_mfma_f32_16x16x32_bf16 v[28:31], v[150:153], v[220:223], v[28:31]
	v_mfma_f32_16x16x32_bf16 v[20:23], v[160:163], v[220:223], v[20:23]
	v_mfma_f32_16x16x32_bf16 v[12:15], v[150:153], v[228:231], v[12:15]
	v_mfma_f32_16x16x32_bf16 v[4:7], v[160:163], v[228:231], v[4:7]
	s_setprio 0
	s_setprio 1
	v_mfma_f32_16x16x32_bf16 v[56:59], v[180:183], v[196:199], v[56:59]
	v_mfma_f32_16x16x32_bf16 v[48:51], v[188:191], v[196:199], v[48:51]
	v_mfma_f32_16x16x32_bf16 v[40:43], v[180:183], v[208:211], v[40:43]
	v_mfma_f32_16x16x32_bf16 v[32:35], v[188:191], v[208:211], v[32:35]
	v_mfma_f32_16x16x32_bf16 v[24:27], v[180:183], v[216:219], v[24:27]
	v_mfma_f32_16x16x32_bf16 v[16:19], v[188:191], v[216:219], v[16:19]
	v_mfma_f32_16x16x32_bf16 v[8:11], v[180:183], v[224:227], v[8:11]
	v_mfma_f32_16x16x32_bf16 v[0:3], v[188:191], v[224:227], v[0:3]
	v_mfma_f32_16x16x32_bf16 v[56:59], v[184:187], v[204:207], v[56:59]
	v_mfma_f32_16x16x32_bf16 v[48:51], v[192:195], v[204:207], v[48:51]
	v_mfma_f32_16x16x32_bf16 v[40:43], v[184:187], v[212:215], v[40:43]
	v_mfma_f32_16x16x32_bf16 v[32:35], v[192:195], v[212:215], v[32:35]
	v_mfma_f32_16x16x32_bf16 v[24:27], v[184:187], v[220:223], v[24:27]
	v_mfma_f32_16x16x32_bf16 v[16:19], v[192:195], v[220:223], v[16:19]
	v_mfma_f32_16x16x32_bf16 v[8:11], v[184:187], v[228:231], v[8:11]
	v_mfma_f32_16x16x32_bf16 v[0:3], v[192:195], v[228:231], v[0:3]
	s_setprio 0
	s_barrier
	s_add_i32 s57, 0, 0x18000
	v_add_u32_e32 v158, s57, v165
	s_add_i32 s58, 0, 0x1c000
	ds_read_b128 v[146:149], v158
	ds_read_b128 v[150:153], v158 offset:1024
	ds_read_b128 v[154:157], v158 offset:2048
	ds_read_b128 v[160:163], v158 offset:3072
	v_add_u32_e32 v158, s58, v165
	ds_read_b128 v[180:183], v158
	ds_read_b128 v[184:187], v158 offset:1024
	ds_read_b128 v[188:191], v158 offset:2048
	ds_read_b128 v[192:195], v158 offset:3072
	s_add_u32 s12, s12, 0x40000
	s_addc_u32 s13, s13, 0
	s_mov_b32 m0, s44
	ds_read_b128 v[196:199], v173 offset:32768
	ds_read_b128 v[204:207], v173 offset:33792
	ds_read_b128 v[208:211], v173 offset:34816
	ds_read_b128 v[212:215], v173 offset:35840
	ds_read_b128 v[216:219], v173 offset:36864
	ds_read_b128 v[220:223], v173 offset:37888
	ds_read_b128 v[224:227], v173 offset:38912
	ds_read_b128 v[228:231], v173 offset:39936
	global_load_lds_dwordx4 v134, s[12:13]
	s_mov_b32 m0, s45
	s_nop 0
	global_load_lds_dwordx4 v130, s[12:13]
	s_waitcnt vmcnt(8)
	s_waitcnt lgkmcnt(0)
	s_barrier
	s_setprio 1
	s_waitcnt lgkmcnt(0)
	v_mfma_f32_16x16x32_bf16 v[124:127], v[146:149], v[196:199], v[124:127]
	v_mfma_f32_16x16x32_bf16 v[116:119], v[154:157], v[196:199], v[116:119]
	v_mfma_f32_16x16x32_bf16 v[108:111], v[146:149], v[208:211], v[108:111]
	v_mfma_f32_16x16x32_bf16 v[100:103], v[154:157], v[208:211], v[100:103]
	v_mfma_f32_16x16x32_bf16 v[92:95], v[146:149], v[216:219], v[92:95]
	v_mfma_f32_16x16x32_bf16 v[84:87], v[154:157], v[216:219], v[84:87]
	v_mfma_f32_16x16x32_bf16 v[76:79], v[146:149], v[224:227], v[76:79]
	v_mfma_f32_16x16x32_bf16 v[68:71], v[154:157], v[224:227], v[68:71]
	v_mfma_f32_16x16x32_bf16 v[124:127], v[150:153], v[204:207], v[124:127]
	v_mfma_f32_16x16x32_bf16 v[116:119], v[160:163], v[204:207], v[116:119]
	v_mfma_f32_16x16x32_bf16 v[108:111], v[150:153], v[212:215], v[108:111]
	v_mfma_f32_16x16x32_bf16 v[100:103], v[160:163], v[212:215], v[100:103]
	v_mfma_f32_16x16x32_bf16 v[92:95], v[150:153], v[220:223], v[92:95]
	v_mfma_f32_16x16x32_bf16 v[84:87], v[160:163], v[220:223], v[84:87]
	v_mfma_f32_16x16x32_bf16 v[76:79], v[150:153], v[228:231], v[76:79]
	v_mfma_f32_16x16x32_bf16 v[68:71], v[160:163], v[228:231], v[68:71]
	s_setprio 0
	s_setprio 1
	v_mfma_f32_16x16x32_bf16 v[120:123], v[180:183], v[196:199], v[120:123]
	v_mfma_f32_16x16x32_bf16 v[112:115], v[188:191], v[196:199], v[112:115]
	v_mfma_f32_16x16x32_bf16 v[104:107], v[180:183], v[208:211], v[104:107]
	v_mfma_f32_16x16x32_bf16 v[96:99], v[188:191], v[208:211], v[96:99]
	v_mfma_f32_16x16x32_bf16 v[88:91], v[180:183], v[216:219], v[88:91]
	v_mfma_f32_16x16x32_bf16 v[80:83], v[188:191], v[216:219], v[80:83]
	v_mfma_f32_16x16x32_bf16 v[72:75], v[180:183], v[224:227], v[72:75]
	v_mfma_f32_16x16x32_bf16 v[64:67], v[188:191], v[224:227], v[64:67]
	v_mfma_f32_16x16x32_bf16 v[120:123], v[184:187], v[204:207], v[120:123]
	v_mfma_f32_16x16x32_bf16 v[112:115], v[192:195], v[204:207], v[112:115]
	v_mfma_f32_16x16x32_bf16 v[104:107], v[184:187], v[212:215], v[104:107]
	v_mfma_f32_16x16x32_bf16 v[96:99], v[192:195], v[212:215], v[96:99]
	v_mfma_f32_16x16x32_bf16 v[88:91], v[184:187], v[220:223], v[88:91]
	v_mfma_f32_16x16x32_bf16 v[80:83], v[192:195], v[220:223], v[80:83]
	v_mfma_f32_16x16x32_bf16 v[72:75], v[184:187], v[228:231], v[72:75]
	v_mfma_f32_16x16x32_bf16 v[64:67], v[192:195], v[228:231], v[64:67]
	s_setprio 0
	s_barrier
	s_add_i32 s12, s57, s23
	v_lshl_add_u64 v[200:201], v[200:201], 0, s[28:29]
	s_mov_b32 m0, s12
	ds_read_b128 v[196:199], v173 offset:49152
	ds_read_b128 v[204:207], v173 offset:50176
	ds_read_b128 v[208:211], v173 offset:51200
	ds_read_b128 v[212:215], v173 offset:52224
	ds_read_b128 v[216:219], v173 offset:53248
	ds_read_b128 v[220:223], v173 offset:54272
	ds_read_b128 v[224:227], v173 offset:55296
	ds_read_b128 v[228:231], v173 offset:56320
	global_load_lds_dwordx4 v[200:201], off
	s_add_i32 m0, s12, 0x2000
	s_add_u32 s4, s4, 0x40080
	v_lshl_add_u64 v[200:201], v[232:233], 0, s[28:29]
	s_addc_u32 s5, s5, 0
	s_add_i32 s12, s58, s23
	global_load_lds_dwordx4 v[200:201], off
	s_mov_b32 m0, s12
	s_nop 0
	global_load_lds_dwordx4 v132, s[4:5]
	s_add_i32 m0, s12, 0x2000
	s_nop 0
	global_load_lds_dwordx4 v128, s[4:5]
	v_lshl_add_u64 v[200:201], v[234:235], 0, s[28:29]
	s_mov_b32 m0, s47
	s_nop 0
	global_load_lds_dwordx4 v[200:201], off
	v_lshl_add_u64 v[200:201], v[236:237], 0, s[28:29]
	s_mov_b32 m0, s48
	s_nop 0
	global_load_lds_dwordx4 v[200:201], off
	s_waitcnt vmcnt(8)
	s_waitcnt lgkmcnt(0)
	s_barrier
	s_setprio 1
	s_waitcnt lgkmcnt(0)
	v_mfma_f32_16x16x32_bf16 v[60:63], v[146:149], v[196:199], v[60:63]
	v_mfma_f32_16x16x32_bf16 v[52:55], v[154:157], v[196:199], v[52:55]
	v_mfma_f32_16x16x32_bf16 v[44:47], v[146:149], v[208:211], v[44:47]
	v_mfma_f32_16x16x32_bf16 v[36:39], v[154:157], v[208:211], v[36:39]
	v_mfma_f32_16x16x32_bf16 v[28:31], v[146:149], v[216:219], v[28:31]
	v_mfma_f32_16x16x32_bf16 v[20:23], v[154:157], v[216:219], v[20:23]
	v_mfma_f32_16x16x32_bf16 v[12:15], v[146:149], v[224:227], v[12:15]
	v_mfma_f32_16x16x32_bf16 v[4:7], v[154:157], v[224:227], v[4:7]
	v_mfma_f32_16x16x32_bf16 v[60:63], v[150:153], v[204:207], v[60:63]
	v_mfma_f32_16x16x32_bf16 v[52:55], v[160:163], v[204:207], v[52:55]
	v_mfma_f32_16x16x32_bf16 v[44:47], v[150:153], v[212:215], v[44:47]
	v_mfma_f32_16x16x32_bf16 v[36:39], v[160:163], v[212:215], v[36:39]
	v_mfma_f32_16x16x32_bf16 v[28:31], v[150:153], v[220:223], v[28:31]
	v_mfma_f32_16x16x32_bf16 v[20:23], v[160:163], v[220:223], v[20:23]
	v_mfma_f32_16x16x32_bf16 v[12:15], v[150:153], v[228:231], v[12:15]
	v_mfma_f32_16x16x32_bf16 v[4:7], v[160:163], v[228:231], v[4:7]
	s_setprio 0
	s_setprio 1
	v_mfma_f32_16x16x32_bf16 v[56:59], v[180:183], v[196:199], v[56:59]
	v_mfma_f32_16x16x32_bf16 v[48:51], v[188:191], v[196:199], v[48:51]
	v_mfma_f32_16x16x32_bf16 v[40:43], v[180:183], v[208:211], v[40:43]
	v_mfma_f32_16x16x32_bf16 v[32:35], v[188:191], v[208:211], v[32:35]
	v_mfma_f32_16x16x32_bf16 v[24:27], v[180:183], v[216:219], v[24:27]
	v_mfma_f32_16x16x32_bf16 v[16:19], v[188:191], v[216:219], v[16:19]
	v_mfma_f32_16x16x32_bf16 v[8:11], v[180:183], v[224:227], v[8:11]
	v_mfma_f32_16x16x32_bf16 v[0:3], v[188:191], v[224:227], v[0:3]
	v_mfma_f32_16x16x32_bf16 v[56:59], v[184:187], v[204:207], v[56:59]
	v_mfma_f32_16x16x32_bf16 v[48:51], v[192:195], v[204:207], v[48:51]
	v_mfma_f32_16x16x32_bf16 v[40:43], v[184:187], v[212:215], v[40:43]
	v_mfma_f32_16x16x32_bf16 v[32:35], v[192:195], v[212:215], v[32:35]
	v_mfma_f32_16x16x32_bf16 v[24:27], v[184:187], v[220:223], v[24:27]
	v_mfma_f32_16x16x32_bf16 v[16:19], v[192:195], v[220:223], v[16:19]
	v_mfma_f32_16x16x32_bf16 v[8:11], v[184:187], v[228:231], v[8:11]
	v_mfma_f32_16x16x32_bf16 v[0:3], v[192:195], v[228:231], v[0:3]
	s_setprio 0
	s_barrier
	s_add_i32 s56, s56, 2
	s_add_u32 s10, s10, 0x100
	s_addc_u32 s11, s11, 0
	s_add_u32 s54, s54, 0x100
	s_addc_u32 s55, s55, 0
	s_cmp_gt_u32 s56, 13
	s_cbranch_scc0 .LBB0_483
	s_and_b64 vcc, exec, s[30:31]
	s_cbranch_vccz .LBB0_486
	s_barrier

.LBB0_559:
	ds_read_b128 v[128:131], v189
	ds_read_b128 v[132:135], v189 offset:1024
	ds_read_b128 v[136:139], v189 offset:2048
	ds_read_b128 v[140:143], v189 offset:3072
	ds_read_b128 v[144:147], v190
	ds_read_b128 v[148:151], v190 offset:1024
	ds_read_b128 v[168:171], v190 offset:2048
	ds_read_b128 v[172:175], v190 offset:3072
	s_add_u32 s4, s22, 0x100
	s_addc_u32 s5, s23, 0
	s_cmp_eq_u32 s57, 40
	s_cselect_b32 s41, s11, s5
	s_cselect_b32 s40, s10, s4
	s_cselect_b32 s39, s37, s56
	s_cselect_b32 s38, s36, s55
	s_add_i32 m0, s43, 0xc000
	ds_read_b128 v[176:179], v191
	ds_read_b128 v[180:183], v191 offset:1024
	ds_read_b128 v[194:197], v191 offset:2048
	ds_read_b128 v[198:201], v191 offset:3072
	ds_read_b128 v[204:207], v191 offset:4096
	ds_read_b128 v[208:211], v191 offset:5120
	ds_read_b128 v[212:215], v191 offset:6144
	ds_read_b128 v[216:219], v191 offset:7168
	global_load_lds_dwordx4 v160, s[22:23]
	s_add_i32 m0, s43, 0xe000
	s_nop 0
	global_load_lds_dwordx4 v162, s[22:23]
	s_waitcnt vmcnt(8)
	s_waitcnt lgkmcnt(0)
	s_barrier
	s_setprio 1
	s_waitcnt lgkmcnt(0)
	v_mfma_f32_16x16x32_bf16 v[124:127], v[128:131], v[176:179], v[124:127]
	v_mfma_f32_16x16x32_bf16 v[120:123], v[136:139], v[176:179], v[120:123]
	v_mfma_f32_16x16x32_bf16 v[108:111], v[128:131], v[194:197], v[108:111]
	v_mfma_f32_16x16x32_bf16 v[104:107], v[136:139], v[194:197], v[104:107]
	v_mfma_f32_16x16x32_bf16 v[92:95], v[128:131], v[204:207], v[92:95]
	v_mfma_f32_16x16x32_bf16 v[88:91], v[136:139], v[204:207], v[88:91]
	v_mfma_f32_16x16x32_bf16 v[76:79], v[128:131], v[212:215], v[76:79]
	v_mfma_f32_16x16x32_bf16 v[72:75], v[136:139], v[212:215], v[72:75]
	v_mfma_f32_16x16x32_bf16 v[124:127], v[132:135], v[180:183], v[124:127]
	v_mfma_f32_16x16x32_bf16 v[120:123], v[140:143], v[180:183], v[120:123]
	v_mfma_f32_16x16x32_bf16 v[108:111], v[132:135], v[198:201], v[108:111]
	v_mfma_f32_16x16x32_bf16 v[104:107], v[140:143], v[198:201], v[104:107]
	v_mfma_f32_16x16x32_bf16 v[92:95], v[132:135], v[208:211], v[92:95]
	v_mfma_f32_16x16x32_bf16 v[88:91], v[140:143], v[208:211], v[88:91]
	v_mfma_f32_16x16x32_bf16 v[76:79], v[132:135], v[216:219], v[76:79]
	v_mfma_f32_16x16x32_bf16 v[72:75], v[140:143], v[216:219], v[72:75]
	s_setprio 0
	s_setprio 1
	v_mfma_f32_16x16x32_bf16 v[116:119], v[144:147], v[176:179], v[116:119]
	v_mfma_f32_16x16x32_bf16 v[112:115], v[168:171], v[176:179], v[112:115]
	v_mfma_f32_16x16x32_bf16 v[100:103], v[144:147], v[194:197], v[100:103]
	v_mfma_f32_16x16x32_bf16 v[96:99], v[168:171], v[194:197], v[96:99]
	v_mfma_f32_16x16x32_bf16 v[84:87], v[144:147], v[204:207], v[84:87]
	v_mfma_f32_16x16x32_bf16 v[80:83], v[168:171], v[204:207], v[80:83]
	v_mfma_f32_16x16x32_bf16 v[68:71], v[144:147], v[212:215], v[68:71]
	v_mfma_f32_16x16x32_bf16 v[64:67], v[168:171], v[212:215], v[64:67]
	v_mfma_f32_16x16x32_bf16 v[116:119], v[148:151], v[180:183], v[116:119]
	v_mfma_f32_16x16x32_bf16 v[112:115], v[172:175], v[180:183], v[112:115]
	v_mfma_f32_16x16x32_bf16 v[100:103], v[148:151], v[198:201], v[100:103]
	v_mfma_f32_16x16x32_bf16 v[96:99], v[172:175], v[198:201], v[96:99]
	v_mfma_f32_16x16x32_bf16 v[84:87], v[148:151], v[208:211], v[84:87]
	v_mfma_f32_16x16x32_bf16 v[80:83], v[172:175], v[208:211], v[80:83]
	v_mfma_f32_16x16x32_bf16 v[68:71], v[148:151], v[216:219], v[68:71]
	v_mfma_f32_16x16x32_bf16 v[64:67], v[172:175], v[216:219], v[64:67]
	s_setprio 0
	s_barrier
	s_add_i32 s22, s49, s42
	v_lshl_add_u64 v[184:185], s[38:39], 0, v[154:155]
	s_mov_b32 m0, s22
	ds_read_b128 v[176:179], v191 offset:16384
	ds_read_b128 v[180:183], v191 offset:17408
	ds_read_b128 v[194:197], v191 offset:18432
	ds_read_b128 v[198:201], v191 offset:19456
	ds_read_b128 v[204:207], v191 offset:20480
	ds_read_b128 v[208:211], v191 offset:21504
	ds_read_b128 v[212:215], v191 offset:22528
	ds_read_b128 v[216:219], v191 offset:23552
	global_load_lds_dwordx4 v154, s[38:39]
	s_add_i32 m0, s22, 0x2000
	s_add_u32 s22, s38, 0xb0000
	v_lshl_add_u64 v[220:221], s[38:39], 0, v[158:159]
	s_addc_u32 s23, s39, 0
	s_add_i32 s58, s50, s42
	global_load_lds_dwordx4 v158, s[38:39]
	s_mov_b32 m0, s58
	v_lshl_add_u64 v[224:225], s[40:41], 0, v[156:157]
	global_load_lds_dwordx4 v154, s[22:23]
	s_add_i32 m0, s58, 0x2000
	s_nop 0
	global_load_lds_dwordx4 v158, s[22:23]
	v_lshl_add_u64 v[222:223], s[40:41], 0, v[152:153]
	s_mov_b32 m0, s43
	s_nop 0
	global_load_lds_dwordx4 v152, s[40:41]
	s_mov_b32 m0, s44
	s_nop 0
	global_load_lds_dwordx4 v156, s[40:41]
	s_waitcnt vmcnt(8)
	s_waitcnt lgkmcnt(0)
	s_barrier
	s_setprio 1
	s_waitcnt lgkmcnt(0)
	v_mfma_f32_16x16x32_bf16 v[60:63], v[128:131], v[176:179], v[60:63]
	v_mfma_f32_16x16x32_bf16 v[56:59], v[136:139], v[176:179], v[56:59]
	v_mfma_f32_16x16x32_bf16 v[44:47], v[128:131], v[194:197], v[44:47]
	v_mfma_f32_16x16x32_bf16 v[40:43], v[136:139], v[194:197], v[40:43]
	v_mfma_f32_16x16x32_bf16 v[28:31], v[128:131], v[204:207], v[28:31]
	v_mfma_f32_16x16x32_bf16 v[24:27], v[136:139], v[204:207], v[24:27]
	v_mfma_f32_16x16x32_bf16 v[12:15], v[128:131], v[212:215], v[12:15]
	v_mfma_f32_16x16x32_bf16 v[8:11], v[136:139], v[212:215], v[8:11]
	v_mfma_f32_16x16x32_bf16 v[60:63], v[132:135], v[180:183], v[60:63]
	v_mfma_f32_16x16x32_bf16 v[56:59], v[140:143], v[180:183], v[56:59]
	v_mfma_f32_16x16x32_bf16 v[44:47], v[132:135], v[198:201], v[44:47]
	v_mfma_f32_16x16x32_bf16 v[40:43], v[140:143], v[198:201], v[40:43]
	v_mfma_f32_16x16x32_bf16 v[28:31], v[132:135], v[208:211], v[28:31]
	v_mfma_f32_16x16x32_bf16 v[24:27], v[140:143], v[208:211], v[24:27]
	v_mfma_f32_16x16x32_bf16 v[12:15], v[132:135], v[216:219], v[12:15]
	v_mfma_f32_16x16x32_bf16 v[8:11], v[140:143], v[216:219], v[8:11]
	s_setprio 0
	s_setprio 1
	v_mfma_f32_16x16x32_bf16 v[52:55], v[144:147], v[176:179], v[52:55]
	v_mfma_f32_16x16x32_bf16 v[48:51], v[168:171], v[176:179], v[48:51]
	v_mfma_f32_16x16x32_bf16 v[36:39], v[144:147], v[194:197], v[36:39]
	v_mfma_f32_16x16x32_bf16 v[32:35], v[168:171], v[194:197], v[32:35]
	v_mfma_f32_16x16x32_bf16 v[20:23], v[144:147], v[204:207], v[20:23]
	v_mfma_f32_16x16x32_bf16 v[16:19], v[168:171], v[204:207], v[16:19]
	v_mfma_f32_16x16x32_bf16 v[4:7], v[144:147], v[212:215], v[4:7]
	v_mfma_f32_16x16x32_bf16 v[0:3], v[168:171], v[212:215], v[0:3]
	v_mfma_f32_16x16x32_bf16 v[52:55], v[148:151], v[180:183], v[52:55]
	v_mfma_f32_16x16x32_bf16 v[48:51], v[172:175], v[180:183], v[48:51]
	v_mfma_f32_16x16x32_bf16 v[36:39], v[148:151], v[198:201], v[36:39]
	v_mfma_f32_16x16x32_bf16 v[32:35], v[172:175], v[198:201], v[32:35]
	v_mfma_f32_16x16x32_bf16 v[20:23], v[148:151], v[208:211], v[20:23]
	v_mfma_f32_16x16x32_bf16 v[16:19], v[172:175], v[208:211], v[16:19]
	v_mfma_f32_16x16x32_bf16 v[4:7], v[148:151], v[216:219], v[4:7]
	v_mfma_f32_16x16x32_bf16 v[0:3], v[172:175], v[216:219], v[0:3]
	s_setprio 0
	s_barrier
	s_add_i32 s58, 0, 0x18000
	s_add_i32 s59, 0, 0x1c000
	v_add_u32_e32 v140, s58, v187
	v_add_u32_e32 v172, s59, v187
	ds_read_b128 v[128:131], v140
	ds_read_b128 v[132:135], v140 offset:1024
	ds_read_b128 v[136:139], v140 offset:2048
	ds_read_b128 v[140:143], v140 offset:3072
	ds_read_b128 v[144:147], v172
	ds_read_b128 v[148:151], v172 offset:1024
	ds_read_b128 v[168:171], v172 offset:2048
	ds_read_b128 v[172:175], v172 offset:3072
	s_add_u32 s22, s40, 0xb0000
	s_addc_u32 s23, s41, 0
	s_mov_b32 m0, s45
	ds_read_b128 v[176:179], v191 offset:32768
	ds_read_b128 v[180:183], v191 offset:33792
	ds_read_b128 v[194:197], v191 offset:34816
	ds_read_b128 v[198:201], v191 offset:35840
	ds_read_b128 v[204:207], v191 offset:36864
	ds_read_b128 v[208:211], v191 offset:37888
	ds_read_b128 v[212:215], v191 offset:38912
	ds_read_b128 v[216:219], v191 offset:39936
	global_load_lds_dwordx4 v152, s[22:23]
	s_mov_b32 m0, s46
	s_nop 0
	global_load_lds_dwordx4 v156, s[22:23]
	s_waitcnt vmcnt(8)
	s_waitcnt lgkmcnt(0)
	s_barrier
	s_setprio 1
	s_waitcnt lgkmcnt(0)
	v_mfma_f32_16x16x32_bf16 v[124:127], v[128:131], v[176:179], v[124:127]
	v_mfma_f32_16x16x32_bf16 v[120:123], v[136:139], v[176:179], v[120:123]
	v_mfma_f32_16x16x32_bf16 v[108:111], v[128:131], v[194:197], v[108:111]
	v_mfma_f32_16x16x32_bf16 v[104:107], v[136:139], v[194:197], v[104:107]
	v_mfma_f32_16x16x32_bf16 v[92:95], v[128:131], v[204:207], v[92:95]
	v_mfma_f32_16x16x32_bf16 v[88:91], v[136:139], v[204:207], v[88:91]
	v_mfma_f32_16x16x32_bf16 v[76:79], v[128:131], v[212:215], v[76:79]
	v_mfma_f32_16x16x32_bf16 v[72:75], v[136:139], v[212:215], v[72:75]
	v_mfma_f32_16x16x32_bf16 v[124:127], v[132:135], v[180:183], v[124:127]
	v_mfma_f32_16x16x32_bf16 v[120:123], v[140:143], v[180:183], v[120:123]
	v_mfma_f32_16x16x32_bf16 v[108:111], v[132:135], v[198:201], v[108:111]
	v_mfma_f32_16x16x32_bf16 v[104:107], v[140:143], v[198:201], v[104:107]
	v_mfma_f32_16x16x32_bf16 v[92:95], v[132:135], v[208:211], v[92:95]
	v_mfma_f32_16x16x32_bf16 v[88:91], v[140:143], v[208:211], v[88:91]
	v_mfma_f32_16x16x32_bf16 v[76:79], v[132:135], v[216:219], v[76:79]
	v_mfma_f32_16x16x32_bf16 v[72:75], v[140:143], v[216:219], v[72:75]
	s_setprio 0
	s_setprio 1
	v_mfma_f32_16x16x32_bf16 v[116:119], v[144:147], v[176:179], v[116:119]
	v_mfma_f32_16x16x32_bf16 v[112:115], v[168:171], v[176:179], v[112:115]
	v_mfma_f32_16x16x32_bf16 v[100:103], v[144:147], v[194:197], v[100:103]
	v_mfma_f32_16x16x32_bf16 v[96:99], v[168:171], v[194:197], v[96:99]
	v_mfma_f32_16x16x32_bf16 v[84:87], v[144:147], v[204:207], v[84:87]
	v_mfma_f32_16x16x32_bf16 v[80:83], v[168:171], v[204:207], v[80:83]
	v_mfma_f32_16x16x32_bf16 v[68:71], v[144:147], v[212:215], v[68:71]
	v_mfma_f32_16x16x32_bf16 v[64:67], v[168:171], v[212:215], v[64:67]
	v_mfma_f32_16x16x32_bf16 v[116:119], v[148:151], v[180:183], v[116:119]
	v_mfma_f32_16x16x32_bf16 v[112:115], v[172:175], v[180:183], v[112:115]
	v_mfma_f32_16x16x32_bf16 v[100:103], v[148:151], v[198:201], v[100:103]
	v_mfma_f32_16x16x32_bf16 v[96:99], v[172:175], v[198:201], v[96:99]
	v_mfma_f32_16x16x32_bf16 v[84:87], v[148:151], v[208:211], v[84:87]
	v_mfma_f32_16x16x32_bf16 v[80:83], v[172:175], v[208:211], v[80:83]
	v_mfma_f32_16x16x32_bf16 v[68:71], v[148:151], v[216:219], v[68:71]
	v_mfma_f32_16x16x32_bf16 v[64:67], v[172:175], v[216:219], v[64:67]
	s_setprio 0
	s_barrier
	s_add_i32 s22, s58, s42
	v_lshl_add_u64 v[184:185], v[184:185], 0, s[30:31]
	s_mov_b32 m0, s22
	ds_read_b128 v[176:179], v191 offset:49152
	ds_read_b128 v[180:183], v191 offset:50176
	ds_read_b128 v[194:197], v191 offset:51200
	ds_read_b128 v[198:201], v191 offset:52224
	ds_read_b128 v[204:207], v191 offset:53248
	ds_read_b128 v[208:211], v191 offset:54272
	ds_read_b128 v[212:215], v191 offset:55296
	ds_read_b128 v[216:219], v191 offset:56320
	global_load_lds_dwordx4 v[184:185], off
	s_add_i32 m0, s22, 0x2000
	s_add_u32 s22, s38, 0xb0080
	v_lshl_add_u64 v[184:185], v[220:221], 0, s[30:31]
	s_addc_u32 s23, s39, 0
	s_add_i32 s38, s59, s42
	global_load_lds_dwordx4 v[184:185], off
	s_mov_b32 m0, s38
	s_nop 0
	global_load_lds_dwordx4 v154, s[22:23]
	s_add_i32 m0, s38, 0x2000
	s_nop 0
	global_load_lds_dwordx4 v158, s[22:23]
	v_lshl_add_u64 v[184:185], v[222:223], 0, s[30:31]
	s_mov_b32 m0, s33
	s_nop 0
	global_load_lds_dwordx4 v[184:185], off
	v_lshl_add_u64 v[184:185], v[224:225], 0, s[30:31]
	s_mov_b32 m0, s48
	s_nop 0
	global_load_lds_dwordx4 v[184:185], off
	s_waitcnt vmcnt(8)
	s_waitcnt lgkmcnt(0)
	s_barrier
	s_setprio 1
	s_waitcnt lgkmcnt(0)
	v_mfma_f32_16x16x32_bf16 v[60:63], v[128:131], v[176:179], v[60:63]
	v_mfma_f32_16x16x32_bf16 v[56:59], v[136:139], v[176:179], v[56:59]
	v_mfma_f32_16x16x32_bf16 v[44:47], v[128:131], v[194:197], v[44:47]
	v_mfma_f32_16x16x32_bf16 v[40:43], v[136:139], v[194:197], v[40:43]
	v_mfma_f32_16x16x32_bf16 v[28:31], v[128:131], v[204:207], v[28:31]
	v_mfma_f32_16x16x32_bf16 v[24:27], v[136:139], v[204:207], v[24:27]
	v_mfma_f32_16x16x32_bf16 v[12:15], v[128:131], v[212:215], v[12:15]
	v_mfma_f32_16x16x32_bf16 v[8:11], v[136:139], v[212:215], v[8:11]
	v_mfma_f32_16x16x32_bf16 v[60:63], v[132:135], v[180:183], v[60:63]
	v_mfma_f32_16x16x32_bf16 v[56:59], v[140:143], v[180:183], v[56:59]
	v_mfma_f32_16x16x32_bf16 v[44:47], v[132:135], v[198:201], v[44:47]
	v_mfma_f32_16x16x32_bf16 v[40:43], v[140:143], v[198:201], v[40:43]
	v_mfma_f32_16x16x32_bf16 v[28:31], v[132:135], v[208:211], v[28:31]
	v_mfma_f32_16x16x32_bf16 v[24:27], v[140:143], v[208:211], v[24:27]
	v_mfma_f32_16x16x32_bf16 v[12:15], v[132:135], v[216:219], v[12:15]
	v_mfma_f32_16x16x32_bf16 v[8:11], v[140:143], v[216:219], v[8:11]
	s_setprio 0
	s_setprio 1
	v_mfma_f32_16x16x32_bf16 v[52:55], v[144:147], v[176:179], v[52:55]
	v_mfma_f32_16x16x32_bf16 v[48:51], v[168:171], v[176:179], v[48:51]
	v_mfma_f32_16x16x32_bf16 v[36:39], v[144:147], v[194:197], v[36:39]
	v_mfma_f32_16x16x32_bf16 v[32:35], v[168:171], v[194:197], v[32:35]
	v_mfma_f32_16x16x32_bf16 v[20:23], v[144:147], v[204:207], v[20:23]
	v_mfma_f32_16x16x32_bf16 v[16:19], v[168:171], v[204:207], v[16:19]
	v_mfma_f32_16x16x32_bf16 v[4:7], v[144:147], v[212:215], v[4:7]
	v_mfma_f32_16x16x32_bf16 v[0:3], v[168:171], v[212:215], v[0:3]
	v_mfma_f32_16x16x32_bf16 v[52:55], v[148:151], v[180:183], v[52:55]
	v_mfma_f32_16x16x32_bf16 v[48:51], v[172:175], v[180:183], v[48:51]
	v_mfma_f32_16x16x32_bf16 v[36:39], v[148:151], v[198:201], v[36:39]
	v_mfma_f32_16x16x32_bf16 v[32:35], v[172:175], v[198:201], v[32:35]
	v_mfma_f32_16x16x32_bf16 v[20:23], v[148:151], v[208:211], v[20:23]
	v_mfma_f32_16x16x32_bf16 v[16:19], v[172:175], v[208:211], v[16:19]
	v_mfma_f32_16x16x32_bf16 v[4:7], v[148:151], v[216:219], v[4:7]
	v_mfma_f32_16x16x32_bf16 v[0:3], v[172:175], v[216:219], v[0:3]
	s_setprio 0
	s_barrier
	s_add_i32 s57, s57, 2
	s_add_u32 s55, s55, 0x100
	s_addc_u32 s56, s56, 0
	s_cmp_gt_u32 s57, 41
	s_mov_b64 s[22:23], s[4:5]
	s_cbranch_scc0 .LBB0_559
	s_and_b64 vcc, exec, s[34:35]
	s_cbranch_vccz .LBB0_562
	s_barrier

.LBB0_643:
	ds_read_b128 v[128:131], v191
	ds_read_b128 v[132:135], v191 offset:1024
	ds_read_b128 v[156:159], v191 offset:2048
	ds_read_b128 v[160:163], v191 offset:3072
	ds_read_b128 v[164:167], v192
	ds_read_b128 v[168:171], v192 offset:1024
	ds_read_b128 v[172:175], v192 offset:2048
	ds_read_b128 v[176:179], v192 offset:3072
	s_add_u32 s4, s22, 0xfffc0080
	s_addc_u32 s5, s23, -1
	s_cmp_eq_u32 s63, 12
	s_cselect_b32 s47, s13, s5
	s_cselect_b32 s46, s17, s4
	s_cselect_b32 s5, s33, s62
	s_cselect_b32 s4, s39, s41
	s_add_i32 m0, s49, 0xc000
	ds_read_b128 v[180:183], v193
	ds_read_b128 v[184:187], v193 offset:1024
	ds_read_b128 v[198:201], v193 offset:2048
	ds_read_b128 v[204:207], v193 offset:3072
	ds_read_b128 v[208:211], v193 offset:4096
	ds_read_b128 v[212:215], v193 offset:5120
	ds_read_b128 v[216:219], v193 offset:6144
	ds_read_b128 v[220:223], v193 offset:7168
	global_load_lds_dwordx4 v148, s[22:23]
	s_add_i32 m0, s49, 0xe000
	s_nop 0
	global_load_lds_dwordx4 v150, s[22:23]
	s_waitcnt vmcnt(8)
	s_waitcnt lgkmcnt(0)
	s_barrier
	s_setprio 1
	s_waitcnt lgkmcnt(0)
	v_mfma_f32_16x16x32_bf16 v[124:127], v[128:131], v[180:183], v[124:127]
	v_mfma_f32_16x16x32_bf16 v[120:123], v[156:159], v[180:183], v[120:123]
	v_mfma_f32_16x16x32_bf16 v[108:111], v[128:131], v[198:201], v[108:111]
	v_mfma_f32_16x16x32_bf16 v[104:107], v[156:159], v[198:201], v[104:107]
	v_mfma_f32_16x16x32_bf16 v[92:95], v[128:131], v[208:211], v[92:95]
	v_mfma_f32_16x16x32_bf16 v[88:91], v[156:159], v[208:211], v[88:91]
	v_mfma_f32_16x16x32_bf16 v[76:79], v[128:131], v[216:219], v[76:79]
	v_mfma_f32_16x16x32_bf16 v[72:75], v[156:159], v[216:219], v[72:75]
	v_mfma_f32_16x16x32_bf16 v[124:127], v[132:135], v[184:187], v[124:127]
	v_mfma_f32_16x16x32_bf16 v[120:123], v[160:163], v[184:187], v[120:123]
	v_mfma_f32_16x16x32_bf16 v[108:111], v[132:135], v[204:207], v[108:111]
	v_mfma_f32_16x16x32_bf16 v[104:107], v[160:163], v[204:207], v[104:107]
	v_mfma_f32_16x16x32_bf16 v[92:95], v[132:135], v[212:215], v[92:95]
	v_mfma_f32_16x16x32_bf16 v[88:91], v[160:163], v[212:215], v[88:91]
	v_mfma_f32_16x16x32_bf16 v[76:79], v[132:135], v[220:223], v[76:79]
	v_mfma_f32_16x16x32_bf16 v[72:75], v[160:163], v[220:223], v[72:75]
	s_setprio 0
	s_setprio 1
	v_mfma_f32_16x16x32_bf16 v[116:119], v[164:167], v[180:183], v[116:119]
	v_mfma_f32_16x16x32_bf16 v[112:115], v[172:175], v[180:183], v[112:115]
	v_mfma_f32_16x16x32_bf16 v[100:103], v[164:167], v[198:201], v[100:103]
	v_mfma_f32_16x16x32_bf16 v[96:99], v[172:175], v[198:201], v[96:99]
	v_mfma_f32_16x16x32_bf16 v[84:87], v[164:167], v[208:211], v[84:87]
	v_mfma_f32_16x16x32_bf16 v[80:83], v[172:175], v[208:211], v[80:83]
	v_mfma_f32_16x16x32_bf16 v[68:71], v[164:167], v[216:219], v[68:71]
	v_mfma_f32_16x16x32_bf16 v[64:67], v[172:175], v[216:219], v[64:67]
	v_mfma_f32_16x16x32_bf16 v[116:119], v[168:171], v[184:187], v[116:119]
	v_mfma_f32_16x16x32_bf16 v[112:115], v[176:179], v[184:187], v[112:115]
	v_mfma_f32_16x16x32_bf16 v[100:103], v[168:171], v[204:207], v[100:103]
	v_mfma_f32_16x16x32_bf16 v[96:99], v[176:179], v[204:207], v[96:99]
	v_mfma_f32_16x16x32_bf16 v[84:87], v[168:171], v[212:215], v[84:87]
	v_mfma_f32_16x16x32_bf16 v[80:83], v[176:179], v[212:215], v[80:83]
	v_mfma_f32_16x16x32_bf16 v[68:71], v[168:171], v[220:223], v[68:71]
	v_mfma_f32_16x16x32_bf16 v[64:67], v[176:179], v[220:223], v[64:67]
	s_setprio 0
	s_barrier
	s_add_i32 s64, s59, s48
	v_lshl_add_u64 v[224:225], s[4:5], 0, v[138:139]
	s_mov_b32 m0, s64
	ds_read_b128 v[180:183], v193 offset:16384
	ds_read_b128 v[184:187], v193 offset:17408
	ds_read_b128 v[198:201], v193 offset:18432
	ds_read_b128 v[204:207], v193 offset:19456
	ds_read_b128 v[208:211], v193 offset:20480
	ds_read_b128 v[212:215], v193 offset:21504
	ds_read_b128 v[216:219], v193 offset:22528
	ds_read_b128 v[220:223], v193 offset:23552
	global_load_lds_dwordx4 v138, s[4:5]
	s_add_i32 m0, s64, 0x2000
	s_add_u32 s64, s4, 0x40000
	v_lshl_add_u64 v[226:227], s[4:5], 0, v[142:143]
	s_addc_u32 s65, s5, 0
	s_add_i32 s66, s60, s48
	global_load_lds_dwordx4 v142, s[4:5]
	s_mov_b32 m0, s66
	v_lshl_add_u64 v[230:231], s[46:47], 0, v[140:141]
	global_load_lds_dwordx4 v138, s[64:65]
	s_add_i32 m0, s66, 0x2000
	s_nop 0
	global_load_lds_dwordx4 v142, s[64:65]
	v_lshl_add_u64 v[228:229], s[46:47], 0, v[136:137]
	s_mov_b32 m0, s49
	s_nop 0
	global_load_lds_dwordx4 v136, s[46:47]
	s_mov_b32 m0, s50
	s_nop 0
	global_load_lds_dwordx4 v140, s[46:47]
	s_waitcnt vmcnt(8)
	s_waitcnt lgkmcnt(0)
	s_barrier
	s_setprio 1
	s_waitcnt lgkmcnt(0)
	v_mfma_f32_16x16x32_bf16 v[60:63], v[128:131], v[180:183], v[60:63]
	v_mfma_f32_16x16x32_bf16 v[56:59], v[156:159], v[180:183], v[56:59]
	v_mfma_f32_16x16x32_bf16 v[44:47], v[128:131], v[198:201], v[44:47]
	v_mfma_f32_16x16x32_bf16 v[40:43], v[156:159], v[198:201], v[40:43]
	v_mfma_f32_16x16x32_bf16 v[28:31], v[128:131], v[208:211], v[28:31]
	v_mfma_f32_16x16x32_bf16 v[24:27], v[156:159], v[208:211], v[24:27]
	v_mfma_f32_16x16x32_bf16 v[12:15], v[128:131], v[216:219], v[12:15]
	v_mfma_f32_16x16x32_bf16 v[8:11], v[156:159], v[216:219], v[8:11]
	v_mfma_f32_16x16x32_bf16 v[60:63], v[132:135], v[184:187], v[60:63]
	v_mfma_f32_16x16x32_bf16 v[56:59], v[160:163], v[184:187], v[56:59]
	v_mfma_f32_16x16x32_bf16 v[44:47], v[132:135], v[204:207], v[44:47]
	v_mfma_f32_16x16x32_bf16 v[40:43], v[160:163], v[204:207], v[40:43]
	v_mfma_f32_16x16x32_bf16 v[28:31], v[132:135], v[212:215], v[28:31]
	v_mfma_f32_16x16x32_bf16 v[24:27], v[160:163], v[212:215], v[24:27]
	v_mfma_f32_16x16x32_bf16 v[12:15], v[132:135], v[220:223], v[12:15]
	v_mfma_f32_16x16x32_bf16 v[8:11], v[160:163], v[220:223], v[8:11]
	s_setprio 0
	s_setprio 1
	v_mfma_f32_16x16x32_bf16 v[52:55], v[164:167], v[180:183], v[52:55]
	v_mfma_f32_16x16x32_bf16 v[48:51], v[172:175], v[180:183], v[48:51]
	v_mfma_f32_16x16x32_bf16 v[36:39], v[164:167], v[198:201], v[36:39]
	v_mfma_f32_16x16x32_bf16 v[32:35], v[172:175], v[198:201], v[32:35]
	v_mfma_f32_16x16x32_bf16 v[20:23], v[164:167], v[208:211], v[20:23]
	v_mfma_f32_16x16x32_bf16 v[16:19], v[172:175], v[208:211], v[16:19]
	v_mfma_f32_16x16x32_bf16 v[4:7], v[164:167], v[216:219], v[4:7]
	v_mfma_f32_16x16x32_bf16 v[0:3], v[172:175], v[216:219], v[0:3]
	v_mfma_f32_16x16x32_bf16 v[52:55], v[168:171], v[184:187], v[52:55]
	v_mfma_f32_16x16x32_bf16 v[48:51], v[176:179], v[184:187], v[48:51]
	v_mfma_f32_16x16x32_bf16 v[36:39], v[168:171], v[204:207], v[36:39]
	v_mfma_f32_16x16x32_bf16 v[32:35], v[176:179], v[204:207], v[32:35]
	v_mfma_f32_16x16x32_bf16 v[20:23], v[168:171], v[212:215], v[20:23]
	v_mfma_f32_16x16x32_bf16 v[16:19], v[176:179], v[212:215], v[16:19]
	v_mfma_f32_16x16x32_bf16 v[4:7], v[168:171], v[220:223], v[4:7]
	v_mfma_f32_16x16x32_bf16 v[0:3], v[176:179], v[220:223], v[0:3]
	s_setprio 0
	s_barrier
	s_add_i32 s64, 0, 0x18000
	v_add_u32_e32 v144, s64, v189
	s_add_i32 s65, 0, 0x1c000
	ds_read_b128 v[128:131], v144
	ds_read_b128 v[132:135], v144 offset:1024
	ds_read_b128 v[156:159], v144 offset:2048
	ds_read_b128 v[160:163], v144 offset:3072
	v_add_u32_e32 v144, s65, v189
	ds_read_b128 v[164:167], v144
	ds_read_b128 v[168:171], v144 offset:1024
	ds_read_b128 v[172:175], v144 offset:2048
	ds_read_b128 v[176:179], v144 offset:3072
	s_add_u32 s46, s46, 0x40000
	s_addc_u32 s47, s47, 0
	s_mov_b32 m0, s51
	ds_read_b128 v[180:183], v193 offset:32768
	ds_read_b128 v[184:187], v193 offset:33792
	ds_read_b128 v[198:201], v193 offset:34816
	ds_read_b128 v[204:207], v193 offset:35840
	ds_read_b128 v[208:211], v193 offset:36864
	ds_read_b128 v[212:215], v193 offset:37888
	ds_read_b128 v[216:219], v193 offset:38912
	ds_read_b128 v[220:223], v193 offset:39936
	global_load_lds_dwordx4 v136, s[46:47]
	s_mov_b32 m0, s52
	s_nop 0
	global_load_lds_dwordx4 v140, s[46:47]
	s_waitcnt vmcnt(8)
	s_waitcnt lgkmcnt(0)
	s_barrier
	s_setprio 1
	s_waitcnt lgkmcnt(0)
	v_mfma_f32_16x16x32_bf16 v[124:127], v[128:131], v[180:183], v[124:127]
	v_mfma_f32_16x16x32_bf16 v[120:123], v[156:159], v[180:183], v[120:123]
	v_mfma_f32_16x16x32_bf16 v[108:111], v[128:131], v[198:201], v[108:111]
	v_mfma_f32_16x16x32_bf16 v[104:107], v[156:159], v[198:201], v[104:107]
	v_mfma_f32_16x16x32_bf16 v[92:95], v[128:131], v[208:211], v[92:95]
	v_mfma_f32_16x16x32_bf16 v[88:91], v[156:159], v[208:211], v[88:91]
	v_mfma_f32_16x16x32_bf16 v[76:79], v[128:131], v[216:219], v[76:79]
	v_mfma_f32_16x16x32_bf16 v[72:75], v[156:159], v[216:219], v[72:75]
	v_mfma_f32_16x16x32_bf16 v[124:127], v[132:135], v[184:187], v[124:127]
	v_mfma_f32_16x16x32_bf16 v[120:123], v[160:163], v[184:187], v[120:123]
	v_mfma_f32_16x16x32_bf16 v[108:111], v[132:135], v[204:207], v[108:111]
	v_mfma_f32_16x16x32_bf16 v[104:107], v[160:163], v[204:207], v[104:107]
	v_mfma_f32_16x16x32_bf16 v[92:95], v[132:135], v[212:215], v[92:95]
	v_mfma_f32_16x16x32_bf16 v[88:91], v[160:163], v[212:215], v[88:91]
	v_mfma_f32_16x16x32_bf16 v[76:79], v[132:135], v[220:223], v[76:79]
	v_mfma_f32_16x16x32_bf16 v[72:75], v[160:163], v[220:223], v[72:75]
	s_setprio 0
	s_setprio 1
	v_mfma_f32_16x16x32_bf16 v[116:119], v[164:167], v[180:183], v[116:119]
	v_mfma_f32_16x16x32_bf16 v[112:115], v[172:175], v[180:183], v[112:115]
	v_mfma_f32_16x16x32_bf16 v[100:103], v[164:167], v[198:201], v[100:103]
	v_mfma_f32_16x16x32_bf16 v[96:99], v[172:175], v[198:201], v[96:99]
	v_mfma_f32_16x16x32_bf16 v[84:87], v[164:167], v[208:211], v[84:87]
	v_mfma_f32_16x16x32_bf16 v[80:83], v[172:175], v[208:211], v[80:83]
	v_mfma_f32_16x16x32_bf16 v[68:71], v[164:167], v[216:219], v[68:71]
	v_mfma_f32_16x16x32_bf16 v[64:67], v[172:175], v[216:219], v[64:67]
	v_mfma_f32_16x16x32_bf16 v[116:119], v[168:171], v[184:187], v[116:119]
	v_mfma_f32_16x16x32_bf16 v[112:115], v[176:179], v[184:187], v[112:115]
	v_mfma_f32_16x16x32_bf16 v[100:103], v[168:171], v[204:207], v[100:103]
	v_mfma_f32_16x16x32_bf16 v[96:99], v[176:179], v[204:207], v[96:99]
	v_mfma_f32_16x16x32_bf16 v[84:87], v[168:171], v[212:215], v[84:87]
	v_mfma_f32_16x16x32_bf16 v[80:83], v[176:179], v[212:215], v[80:83]
	v_mfma_f32_16x16x32_bf16 v[68:71], v[168:171], v[220:223], v[68:71]
	v_mfma_f32_16x16x32_bf16 v[64:67], v[176:179], v[220:223], v[64:67]
	s_setprio 0
	s_barrier
	s_add_i32 s46, s64, s48
	v_lshl_add_u64 v[224:225], v[224:225], 0, s[30:31]
	s_mov_b32 m0, s46
	ds_read_b128 v[180:183], v193 offset:49152
	ds_read_b128 v[184:187], v193 offset:50176
	ds_read_b128 v[198:201], v193 offset:51200
	ds_read_b128 v[204:207], v193 offset:52224
	ds_read_b128 v[208:211], v193 offset:53248
	ds_read_b128 v[212:215], v193 offset:54272
	ds_read_b128 v[216:219], v193 offset:55296
	ds_read_b128 v[220:223], v193 offset:56320
	global_load_lds_dwordx4 v[224:225], off
	s_add_i32 m0, s46, 0x2000
	s_add_u32 s4, s4, 0x40080
	v_lshl_add_u64 v[224:225], v[226:227], 0, s[30:31]
	s_addc_u32 s5, s5, 0
	s_add_i32 s46, s65, s48
	global_load_lds_dwordx4 v[224:225], off
	s_mov_b32 m0, s46
	s_nop 0
	global_load_lds_dwordx4 v138, s[4:5]
	s_add_i32 m0, s46, 0x2000
	s_nop 0
	global_load_lds_dwordx4 v142, s[4:5]
	v_lshl_add_u64 v[224:225], v[228:229], 0, s[30:31]
	s_mov_b32 m0, s56
	s_nop 0
	global_load_lds_dwordx4 v[224:225], off
	v_lshl_add_u64 v[224:225], v[230:231], 0, s[30:31]
	s_mov_b32 m0, s57
	s_nop 0
	global_load_lds_dwordx4 v[224:225], off
	s_waitcnt vmcnt(8)
	s_waitcnt lgkmcnt(0)
	s_barrier
	s_setprio 1
	s_waitcnt lgkmcnt(0)
	v_mfma_f32_16x16x32_bf16 v[60:63], v[128:131], v[180:183], v[60:63]
	v_mfma_f32_16x16x32_bf16 v[56:59], v[156:159], v[180:183], v[56:59]
	v_mfma_f32_16x16x32_bf16 v[44:47], v[128:131], v[198:201], v[44:47]
	v_mfma_f32_16x16x32_bf16 v[40:43], v[156:159], v[198:201], v[40:43]
	v_mfma_f32_16x16x32_bf16 v[28:31], v[128:131], v[208:211], v[28:31]
	v_mfma_f32_16x16x32_bf16 v[24:27], v[156:159], v[208:211], v[24:27]
	v_mfma_f32_16x16x32_bf16 v[12:15], v[128:131], v[216:219], v[12:15]
	v_mfma_f32_16x16x32_bf16 v[8:11], v[156:159], v[216:219], v[8:11]
	v_mfma_f32_16x16x32_bf16 v[60:63], v[132:135], v[184:187], v[60:63]
	v_mfma_f32_16x16x32_bf16 v[56:59], v[160:163], v[184:187], v[56:59]
	v_mfma_f32_16x16x32_bf16 v[44:47], v[132:135], v[204:207], v[44:47]
	v_mfma_f32_16x16x32_bf16 v[40:43], v[160:163], v[204:207], v[40:43]
	v_mfma_f32_16x16x32_bf16 v[28:31], v[132:135], v[212:215], v[28:31]
	v_mfma_f32_16x16x32_bf16 v[24:27], v[160:163], v[212:215], v[24:27]
	v_mfma_f32_16x16x32_bf16 v[12:15], v[132:135], v[220:223], v[12:15]
	v_mfma_f32_16x16x32_bf16 v[8:11], v[160:163], v[220:223], v[8:11]
	s_setprio 0
	s_setprio 1
	v_mfma_f32_16x16x32_bf16 v[52:55], v[164:167], v[180:183], v[52:55]
	v_mfma_f32_16x16x32_bf16 v[48:51], v[172:175], v[180:183], v[48:51]
	v_mfma_f32_16x16x32_bf16 v[36:39], v[164:167], v[198:201], v[36:39]
	v_mfma_f32_16x16x32_bf16 v[32:35], v[172:175], v[198:201], v[32:35]
	v_mfma_f32_16x16x32_bf16 v[20:23], v[164:167], v[208:211], v[20:23]
	v_mfma_f32_16x16x32_bf16 v[16:19], v[172:175], v[208:211], v[16:19]
	v_mfma_f32_16x16x32_bf16 v[4:7], v[164:167], v[216:219], v[4:7]
	v_mfma_f32_16x16x32_bf16 v[0:3], v[172:175], v[216:219], v[0:3]
	v_mfma_f32_16x16x32_bf16 v[52:55], v[168:171], v[184:187], v[52:55]
	v_mfma_f32_16x16x32_bf16 v[48:51], v[176:179], v[184:187], v[48:51]
	v_mfma_f32_16x16x32_bf16 v[36:39], v[168:171], v[204:207], v[36:39]
	v_mfma_f32_16x16x32_bf16 v[32:35], v[176:179], v[204:207], v[32:35]
	v_mfma_f32_16x16x32_bf16 v[20:23], v[168:171], v[212:215], v[20:23]
	v_mfma_f32_16x16x32_bf16 v[16:19], v[176:179], v[212:215], v[16:19]
	v_mfma_f32_16x16x32_bf16 v[4:7], v[168:171], v[220:223], v[4:7]
	v_mfma_f32_16x16x32_bf16 v[0:3], v[176:179], v[220:223], v[0:3]
	s_setprio 0
	s_barrier
	s_add_i32 s63, s63, 2
	s_add_u32 s22, s22, 0x100
	s_addc_u32 s23, s23, 0
	s_add_u32 s41, s41, 0x100
	s_addc_u32 s62, s62, 0
	s_cmp_gt_u32 s63, 13
	s_cbranch_scc0 .LBB0_643
	s_and_b64 vcc, exec, s[34:35]
	s_cbranch_vccz .LBB0_646
	s_barrier

.LBB0_966:
	ds_read_b128 v[128:131], v189
	ds_read_b128 v[132:135], v189 offset:1024
	ds_read_b128 v[136:139], v189 offset:2048
	ds_read_b128 v[140:143], v189 offset:3072
	ds_read_b128 v[144:147], v190
	ds_read_b128 v[148:151], v190 offset:1024
	ds_read_b128 v[168:171], v190 offset:2048
	ds_read_b128 v[172:175], v190 offset:3072
	s_add_u32 s4, s22, 0xfffc0080
	s_addc_u32 s5, s23, -1
	s_cmp_eq_u32 s58, 12
	s_cselect_b32 s43, s35, s5
	s_cselect_b32 s42, s41, s4
	s_cselect_b32 s5, s31, s57
	s_cselect_b32 s4, s55, s56
	s_add_i32 m0, s46, 0xc000
	ds_read_b128 v[176:179], v191
	ds_read_b128 v[180:183], v191 offset:1024
	ds_read_b128 v[192:195], v191 offset:2048
	ds_read_b128 v[198:201], v191 offset:3072
	ds_read_b128 v[204:207], v191 offset:4096
	ds_read_b128 v[208:211], v191 offset:5120
	ds_read_b128 v[212:215], v191 offset:6144
	ds_read_b128 v[216:219], v191 offset:7168
	global_load_lds_dwordx4 v160, s[22:23]
	s_add_i32 m0, s46, 0xe000
	s_nop 0
	global_load_lds_dwordx4 v162, s[22:23]
	s_waitcnt vmcnt(8)
	s_waitcnt lgkmcnt(0)
	s_barrier
	s_setprio 1
	s_waitcnt lgkmcnt(0)
	v_mfma_f32_16x16x32_bf16 v[124:127], v[128:131], v[176:179], v[124:127]
	v_mfma_f32_16x16x32_bf16 v[120:123], v[136:139], v[176:179], v[120:123]
	v_mfma_f32_16x16x32_bf16 v[108:111], v[128:131], v[192:195], v[108:111]
	v_mfma_f32_16x16x32_bf16 v[104:107], v[136:139], v[192:195], v[104:107]
	v_mfma_f32_16x16x32_bf16 v[92:95], v[128:131], v[204:207], v[92:95]
	v_mfma_f32_16x16x32_bf16 v[88:91], v[136:139], v[204:207], v[88:91]
	v_mfma_f32_16x16x32_bf16 v[76:79], v[128:131], v[212:215], v[76:79]
	v_mfma_f32_16x16x32_bf16 v[72:75], v[136:139], v[212:215], v[72:75]
	v_mfma_f32_16x16x32_bf16 v[124:127], v[132:135], v[180:183], v[124:127]
	v_mfma_f32_16x16x32_bf16 v[120:123], v[140:143], v[180:183], v[120:123]
	v_mfma_f32_16x16x32_bf16 v[108:111], v[132:135], v[198:201], v[108:111]
	v_mfma_f32_16x16x32_bf16 v[104:107], v[140:143], v[198:201], v[104:107]
	v_mfma_f32_16x16x32_bf16 v[92:95], v[132:135], v[208:211], v[92:95]
	v_mfma_f32_16x16x32_bf16 v[88:91], v[140:143], v[208:211], v[88:91]
	v_mfma_f32_16x16x32_bf16 v[76:79], v[132:135], v[216:219], v[76:79]
	v_mfma_f32_16x16x32_bf16 v[72:75], v[140:143], v[216:219], v[72:75]
	s_setprio 0
	s_setprio 1
	v_mfma_f32_16x16x32_bf16 v[116:119], v[144:147], v[176:179], v[116:119]
	v_mfma_f32_16x16x32_bf16 v[112:115], v[168:171], v[176:179], v[112:115]
	v_mfma_f32_16x16x32_bf16 v[100:103], v[144:147], v[192:195], v[100:103]
	v_mfma_f32_16x16x32_bf16 v[96:99], v[168:171], v[192:195], v[96:99]
	v_mfma_f32_16x16x32_bf16 v[84:87], v[144:147], v[204:207], v[84:87]
	v_mfma_f32_16x16x32_bf16 v[80:83], v[168:171], v[204:207], v[80:83]
	v_mfma_f32_16x16x32_bf16 v[68:71], v[144:147], v[212:215], v[68:71]
	v_mfma_f32_16x16x32_bf16 v[64:67], v[168:171], v[212:215], v[64:67]
	v_mfma_f32_16x16x32_bf16 v[116:119], v[148:151], v[180:183], v[116:119]
	v_mfma_f32_16x16x32_bf16 v[112:115], v[172:175], v[180:183], v[112:115]
	v_mfma_f32_16x16x32_bf16 v[100:103], v[148:151], v[198:201], v[100:103]
	v_mfma_f32_16x16x32_bf16 v[96:99], v[172:175], v[198:201], v[96:99]
	v_mfma_f32_16x16x32_bf16 v[84:87], v[148:151], v[208:211], v[84:87]
	v_mfma_f32_16x16x32_bf16 v[80:83], v[172:175], v[208:211], v[80:83]
	v_mfma_f32_16x16x32_bf16 v[68:71], v[148:151], v[216:219], v[68:71]
	v_mfma_f32_16x16x32_bf16 v[64:67], v[172:175], v[216:219], v[64:67]
	s_setprio 0
	s_barrier
	s_add_i32 s59, s52, s45
	v_lshl_add_u64 v[184:185], s[4:5], 0, v[154:155]
	s_mov_b32 m0, s59
	ds_read_b128 v[176:179], v191 offset:16384
	ds_read_b128 v[180:183], v191 offset:17408
	ds_read_b128 v[192:195], v191 offset:18432
	ds_read_b128 v[198:201], v191 offset:19456
	ds_read_b128 v[204:207], v191 offset:20480
	ds_read_b128 v[208:211], v191 offset:21504
	ds_read_b128 v[212:215], v191 offset:22528
	ds_read_b128 v[216:219], v191 offset:23552
	global_load_lds_dwordx4 v154, s[4:5]
	s_add_i32 m0, s59, 0x2000
	s_add_u32 s60, s4, 0x40000
	v_lshl_add_u64 v[220:221], s[4:5], 0, v[158:159]
	s_addc_u32 s61, s5, 0
	s_add_i32 s59, s53, s45
	global_load_lds_dwordx4 v158, s[4:5]
	s_mov_b32 m0, s59
	v_lshl_add_u64 v[224:225], s[42:43], 0, v[156:157]
	global_load_lds_dwordx4 v154, s[60:61]
	s_add_i32 m0, s59, 0x2000
	s_nop 0
	global_load_lds_dwordx4 v158, s[60:61]
	v_lshl_add_u64 v[222:223], s[42:43], 0, v[152:153]
	s_mov_b32 m0, s46
	s_nop 0
	global_load_lds_dwordx4 v152, s[42:43]
	s_mov_b32 m0, s33
	s_nop 0
	global_load_lds_dwordx4 v156, s[42:43]
	s_waitcnt vmcnt(8)
	s_waitcnt lgkmcnt(0)
	s_barrier
	s_setprio 1
	s_waitcnt lgkmcnt(0)
	v_mfma_f32_16x16x32_bf16 v[60:63], v[128:131], v[176:179], v[60:63]
	v_mfma_f32_16x16x32_bf16 v[56:59], v[136:139], v[176:179], v[56:59]
	v_mfma_f32_16x16x32_bf16 v[44:47], v[128:131], v[192:195], v[44:47]
	v_mfma_f32_16x16x32_bf16 v[40:43], v[136:139], v[192:195], v[40:43]
	v_mfma_f32_16x16x32_bf16 v[28:31], v[128:131], v[204:207], v[28:31]
	v_mfma_f32_16x16x32_bf16 v[24:27], v[136:139], v[204:207], v[24:27]
	v_mfma_f32_16x16x32_bf16 v[12:15], v[128:131], v[212:215], v[12:15]
	v_mfma_f32_16x16x32_bf16 v[8:11], v[136:139], v[212:215], v[8:11]
	v_mfma_f32_16x16x32_bf16 v[60:63], v[132:135], v[180:183], v[60:63]
	v_mfma_f32_16x16x32_bf16 v[56:59], v[140:143], v[180:183], v[56:59]
	v_mfma_f32_16x16x32_bf16 v[44:47], v[132:135], v[198:201], v[44:47]
	v_mfma_f32_16x16x32_bf16 v[40:43], v[140:143], v[198:201], v[40:43]
	v_mfma_f32_16x16x32_bf16 v[28:31], v[132:135], v[208:211], v[28:31]
	v_mfma_f32_16x16x32_bf16 v[24:27], v[140:143], v[208:211], v[24:27]
	v_mfma_f32_16x16x32_bf16 v[12:15], v[132:135], v[216:219], v[12:15]
	v_mfma_f32_16x16x32_bf16 v[8:11], v[140:143], v[216:219], v[8:11]
	s_setprio 0
	s_setprio 1
	v_mfma_f32_16x16x32_bf16 v[52:55], v[144:147], v[176:179], v[52:55]
	v_mfma_f32_16x16x32_bf16 v[48:51], v[168:171], v[176:179], v[48:51]
	v_mfma_f32_16x16x32_bf16 v[36:39], v[144:147], v[192:195], v[36:39]
	v_mfma_f32_16x16x32_bf16 v[32:35], v[168:171], v[192:195], v[32:35]
	v_mfma_f32_16x16x32_bf16 v[20:23], v[144:147], v[204:207], v[20:23]
	v_mfma_f32_16x16x32_bf16 v[16:19], v[168:171], v[204:207], v[16:19]
	v_mfma_f32_16x16x32_bf16 v[4:7], v[144:147], v[212:215], v[4:7]
	v_mfma_f32_16x16x32_bf16 v[0:3], v[168:171], v[212:215], v[0:3]
	v_mfma_f32_16x16x32_bf16 v[52:55], v[148:151], v[180:183], v[52:55]
	v_mfma_f32_16x16x32_bf16 v[48:51], v[172:175], v[180:183], v[48:51]
	v_mfma_f32_16x16x32_bf16 v[36:39], v[148:151], v[198:201], v[36:39]
	v_mfma_f32_16x16x32_bf16 v[32:35], v[172:175], v[198:201], v[32:35]
	v_mfma_f32_16x16x32_bf16 v[20:23], v[148:151], v[208:211], v[20:23]
	v_mfma_f32_16x16x32_bf16 v[16:19], v[172:175], v[208:211], v[16:19]
	v_mfma_f32_16x16x32_bf16 v[4:7], v[148:151], v[216:219], v[4:7]
	v_mfma_f32_16x16x32_bf16 v[0:3], v[172:175], v[216:219], v[0:3]
	s_setprio 0
	s_barrier
	s_add_i32 s59, 0, 0x18000
	s_add_i32 s60, 0, 0x1c000
	v_add_u32_e32 v140, s59, v187
	v_add_u32_e32 v172, s60, v187
	ds_read_b128 v[128:131], v140
	ds_read_b128 v[132:135], v140 offset:1024
	ds_read_b128 v[136:139], v140 offset:2048
	ds_read_b128 v[140:143], v140 offset:3072
	ds_read_b128 v[144:147], v172
	ds_read_b128 v[148:151], v172 offset:1024
	ds_read_b128 v[168:171], v172 offset:2048
	ds_read_b128 v[172:175], v172 offset:3072
	s_add_u32 s42, s42, 0x40000
	s_addc_u32 s43, s43, 0
	s_mov_b32 m0, s47
	ds_read_b128 v[176:179], v191 offset:32768
	ds_read_b128 v[180:183], v191 offset:33792
	ds_read_b128 v[192:195], v191 offset:34816
	ds_read_b128 v[198:201], v191 offset:35840
	ds_read_b128 v[204:207], v191 offset:36864
	ds_read_b128 v[208:211], v191 offset:37888
	ds_read_b128 v[212:215], v191 offset:38912
	ds_read_b128 v[216:219], v191 offset:39936
	global_load_lds_dwordx4 v152, s[42:43]
	s_mov_b32 m0, s48
	s_nop 0
	global_load_lds_dwordx4 v156, s[42:43]
	s_waitcnt vmcnt(8)
	s_waitcnt lgkmcnt(0)
	s_barrier
	s_setprio 1
	s_waitcnt lgkmcnt(0)
	v_mfma_f32_16x16x32_bf16 v[124:127], v[128:131], v[176:179], v[124:127]
	v_mfma_f32_16x16x32_bf16 v[120:123], v[136:139], v[176:179], v[120:123]
	v_mfma_f32_16x16x32_bf16 v[108:111], v[128:131], v[192:195], v[108:111]
	v_mfma_f32_16x16x32_bf16 v[104:107], v[136:139], v[192:195], v[104:107]
	v_mfma_f32_16x16x32_bf16 v[92:95], v[128:131], v[204:207], v[92:95]
	v_mfma_f32_16x16x32_bf16 v[88:91], v[136:139], v[204:207], v[88:91]
	v_mfma_f32_16x16x32_bf16 v[76:79], v[128:131], v[212:215], v[76:79]
	v_mfma_f32_16x16x32_bf16 v[72:75], v[136:139], v[212:215], v[72:75]
	v_mfma_f32_16x16x32_bf16 v[124:127], v[132:135], v[180:183], v[124:127]
	v_mfma_f32_16x16x32_bf16 v[120:123], v[140:143], v[180:183], v[120:123]
	v_mfma_f32_16x16x32_bf16 v[108:111], v[132:135], v[198:201], v[108:111]
	v_mfma_f32_16x16x32_bf16 v[104:107], v[140:143], v[198:201], v[104:107]
	v_mfma_f32_16x16x32_bf16 v[92:95], v[132:135], v[208:211], v[92:95]
	v_mfma_f32_16x16x32_bf16 v[88:91], v[140:143], v[208:211], v[88:91]
	v_mfma_f32_16x16x32_bf16 v[76:79], v[132:135], v[216:219], v[76:79]
	v_mfma_f32_16x16x32_bf16 v[72:75], v[140:143], v[216:219], v[72:75]
	s_setprio 0
	s_setprio 1
	v_mfma_f32_16x16x32_bf16 v[116:119], v[144:147], v[176:179], v[116:119]
	v_mfma_f32_16x16x32_bf16 v[112:115], v[168:171], v[176:179], v[112:115]
	v_mfma_f32_16x16x32_bf16 v[100:103], v[144:147], v[192:195], v[100:103]
	v_mfma_f32_16x16x32_bf16 v[96:99], v[168:171], v[192:195], v[96:99]
	v_mfma_f32_16x16x32_bf16 v[84:87], v[144:147], v[204:207], v[84:87]
	v_mfma_f32_16x16x32_bf16 v[80:83], v[168:171], v[204:207], v[80:83]
	v_mfma_f32_16x16x32_bf16 v[68:71], v[144:147], v[212:215], v[68:71]
	v_mfma_f32_16x16x32_bf16 v[64:67], v[168:171], v[212:215], v[64:67]
	v_mfma_f32_16x16x32_bf16 v[116:119], v[148:151], v[180:183], v[116:119]
	v_mfma_f32_16x16x32_bf16 v[112:115], v[172:175], v[180:183], v[112:115]
	v_mfma_f32_16x16x32_bf16 v[100:103], v[148:151], v[198:201], v[100:103]
	v_mfma_f32_16x16x32_bf16 v[96:99], v[172:175], v[198:201], v[96:99]
	v_mfma_f32_16x16x32_bf16 v[84:87], v[148:151], v[208:211], v[84:87]
	v_mfma_f32_16x16x32_bf16 v[80:83], v[172:175], v[208:211], v[80:83]
	v_mfma_f32_16x16x32_bf16 v[68:71], v[148:151], v[216:219], v[68:71]
	v_mfma_f32_16x16x32_bf16 v[64:67], v[172:175], v[216:219], v[64:67]
	s_setprio 0
	s_barrier
	s_add_i32 s42, s59, s45
	v_lshl_add_u64 v[184:185], v[184:185], 0, s[26:27]
	s_mov_b32 m0, s42
	ds_read_b128 v[176:179], v191 offset:49152
	ds_read_b128 v[180:183], v191 offset:50176
	ds_read_b128 v[192:195], v191 offset:51200
	ds_read_b128 v[198:201], v191 offset:52224
	ds_read_b128 v[204:207], v191 offset:53248
	ds_read_b128 v[208:211], v191 offset:54272
	ds_read_b128 v[212:215], v191 offset:55296
	ds_read_b128 v[216:219], v191 offset:56320
	global_load_lds_dwordx4 v[184:185], off
	s_add_i32 m0, s42, 0x2000
	s_add_u32 s4, s4, 0x40080
	v_lshl_add_u64 v[184:185], v[220:221], 0, s[26:27]
	s_addc_u32 s5, s5, 0
	s_add_i32 s42, s60, s45
	global_load_lds_dwordx4 v[184:185], off
	s_mov_b32 m0, s42
	s_nop 0
	global_load_lds_dwordx4 v154, s[4:5]
	s_add_i32 m0, s42, 0x2000
	s_nop 0
	global_load_lds_dwordx4 v158, s[4:5]
	v_lshl_add_u64 v[184:185], v[222:223], 0, s[26:27]
	s_mov_b32 m0, s50
	s_nop 0
	global_load_lds_dwordx4 v[184:185], off
	v_lshl_add_u64 v[184:185], v[224:225], 0, s[26:27]
	s_mov_b32 m0, s51
	s_nop 0
	global_load_lds_dwordx4 v[184:185], off
	s_waitcnt vmcnt(8)
	s_waitcnt lgkmcnt(0)
	s_barrier
	s_setprio 1
	s_waitcnt lgkmcnt(0)
	v_mfma_f32_16x16x32_bf16 v[60:63], v[128:131], v[176:179], v[60:63]
	v_mfma_f32_16x16x32_bf16 v[56:59], v[136:139], v[176:179], v[56:59]
	v_mfma_f32_16x16x32_bf16 v[44:47], v[128:131], v[192:195], v[44:47]
	v_mfma_f32_16x16x32_bf16 v[40:43], v[136:139], v[192:195], v[40:43]
	v_mfma_f32_16x16x32_bf16 v[28:31], v[128:131], v[204:207], v[28:31]
	v_mfma_f32_16x16x32_bf16 v[24:27], v[136:139], v[204:207], v[24:27]
	v_mfma_f32_16x16x32_bf16 v[12:15], v[128:131], v[212:215], v[12:15]
	v_mfma_f32_16x16x32_bf16 v[8:11], v[136:139], v[212:215], v[8:11]
	v_mfma_f32_16x16x32_bf16 v[60:63], v[132:135], v[180:183], v[60:63]
	v_mfma_f32_16x16x32_bf16 v[56:59], v[140:143], v[180:183], v[56:59]
	v_mfma_f32_16x16x32_bf16 v[44:47], v[132:135], v[198:201], v[44:47]
	v_mfma_f32_16x16x32_bf16 v[40:43], v[140:143], v[198:201], v[40:43]
	v_mfma_f32_16x16x32_bf16 v[28:31], v[132:135], v[208:211], v[28:31]
	v_mfma_f32_16x16x32_bf16 v[24:27], v[140:143], v[208:211], v[24:27]
	v_mfma_f32_16x16x32_bf16 v[12:15], v[132:135], v[216:219], v[12:15]
	v_mfma_f32_16x16x32_bf16 v[8:11], v[140:143], v[216:219], v[8:11]
	s_setprio 0
	s_setprio 1
	v_mfma_f32_16x16x32_bf16 v[52:55], v[144:147], v[176:179], v[52:55]
	v_mfma_f32_16x16x32_bf16 v[48:51], v[168:171], v[176:179], v[48:51]
	v_mfma_f32_16x16x32_bf16 v[36:39], v[144:147], v[192:195], v[36:39]
	v_mfma_f32_16x16x32_bf16 v[32:35], v[168:171], v[192:195], v[32:35]
	v_mfma_f32_16x16x32_bf16 v[20:23], v[144:147], v[204:207], v[20:23]
	v_mfma_f32_16x16x32_bf16 v[16:19], v[168:171], v[204:207], v[16:19]
	v_mfma_f32_16x16x32_bf16 v[4:7], v[144:147], v[212:215], v[4:7]
	v_mfma_f32_16x16x32_bf16 v[0:3], v[168:171], v[212:215], v[0:3]
	v_mfma_f32_16x16x32_bf16 v[52:55], v[148:151], v[180:183], v[52:55]
	v_mfma_f32_16x16x32_bf16 v[48:51], v[172:175], v[180:183], v[48:51]
	v_mfma_f32_16x16x32_bf16 v[36:39], v[148:151], v[198:201], v[36:39]
	v_mfma_f32_16x16x32_bf16 v[32:35], v[172:175], v[198:201], v[32:35]
	v_mfma_f32_16x16x32_bf16 v[20:23], v[148:151], v[208:211], v[20:23]
	v_mfma_f32_16x16x32_bf16 v[16:19], v[172:175], v[208:211], v[16:19]
	v_mfma_f32_16x16x32_bf16 v[4:7], v[148:151], v[216:219], v[4:7]
	v_mfma_f32_16x16x32_bf16 v[0:3], v[172:175], v[216:219], v[0:3]
	s_setprio 0
	s_barrier
	s_add_i32 s58, s58, 2
	s_add_u32 s22, s22, 0x100
	s_addc_u32 s23, s23, 0
	s_add_u32 s56, s56, 0x100
	s_addc_u32 s57, s57, 0
	s_cmp_gt_u32 s58, 13
	s_cbranch_scc0 .LBB0_966
	s_and_b64 vcc, exec, s[28:29]
	s_cbranch_vccz .LBB0_969
	s_barrier

.LBB0_1048:
	ds_read_b128 v[146:149], v169
	ds_read_b128 v[150:153], v169 offset:1024
	ds_read_b128 v[154:157], v169 offset:2048
	ds_read_b128 v[160:163], v169 offset:3072
	ds_read_b128 v[178:181], v171
	ds_read_b128 v[182:185], v171 offset:1024
	ds_read_b128 v[186:189], v171 offset:2048
	ds_read_b128 v[190:193], v171 offset:3072
	s_add_u32 s4, s10, 0xfffc0080
	s_addc_u32 s5, s11, -1
	s_cmp_eq_u32 s55, 12
	s_cselect_b32 s13, s9, s5
	s_cselect_b32 s12, s31, s4
	s_cselect_b32 s5, s29, s54
	s_cselect_b32 s4, s52, s53
	s_add_i32 m0, s41, 0xc000
	ds_read_b128 v[198:201], v173
	ds_read_b128 v[204:207], v173 offset:1024
	ds_read_b128 v[208:211], v173 offset:2048
	ds_read_b128 v[212:215], v173 offset:3072
	ds_read_b128 v[216:219], v173 offset:4096
	ds_read_b128 v[220:223], v173 offset:5120
	ds_read_b128 v[224:227], v173 offset:6144
	ds_read_b128 v[228:231], v173 offset:7168
	global_load_lds_dwordx4 v138, s[10:11]
	s_add_i32 m0, s41, 0xe000
	s_nop 0
	global_load_lds_dwordx4 v140, s[10:11]
	s_waitcnt vmcnt(8)
	s_waitcnt lgkmcnt(0)
	s_barrier
	s_setprio 1
	s_waitcnt lgkmcnt(0)
	v_mfma_f32_16x16x32_bf16 v[124:127], v[146:149], v[198:201], v[124:127]
	v_mfma_f32_16x16x32_bf16 v[116:119], v[154:157], v[198:201], v[116:119]
	v_mfma_f32_16x16x32_bf16 v[108:111], v[146:149], v[208:211], v[108:111]
	v_mfma_f32_16x16x32_bf16 v[100:103], v[154:157], v[208:211], v[100:103]
	v_mfma_f32_16x16x32_bf16 v[92:95], v[146:149], v[216:219], v[92:95]
	v_mfma_f32_16x16x32_bf16 v[84:87], v[154:157], v[216:219], v[84:87]
	v_mfma_f32_16x16x32_bf16 v[76:79], v[146:149], v[224:227], v[76:79]
	v_mfma_f32_16x16x32_bf16 v[68:71], v[154:157], v[224:227], v[68:71]
	v_mfma_f32_16x16x32_bf16 v[124:127], v[150:153], v[204:207], v[124:127]
	v_mfma_f32_16x16x32_bf16 v[116:119], v[160:163], v[204:207], v[116:119]
	v_mfma_f32_16x16x32_bf16 v[108:111], v[150:153], v[212:215], v[108:111]
	v_mfma_f32_16x16x32_bf16 v[100:103], v[160:163], v[212:215], v[100:103]
	v_mfma_f32_16x16x32_bf16 v[92:95], v[150:153], v[220:223], v[92:95]
	v_mfma_f32_16x16x32_bf16 v[84:87], v[160:163], v[220:223], v[84:87]
	v_mfma_f32_16x16x32_bf16 v[76:79], v[150:153], v[228:231], v[76:79]
	v_mfma_f32_16x16x32_bf16 v[68:71], v[160:163], v[228:231], v[68:71]
	s_setprio 0
	s_setprio 1
	v_mfma_f32_16x16x32_bf16 v[120:123], v[178:181], v[198:201], v[120:123]
	v_mfma_f32_16x16x32_bf16 v[112:115], v[186:189], v[198:201], v[112:115]
	v_mfma_f32_16x16x32_bf16 v[104:107], v[178:181], v[208:211], v[104:107]
	v_mfma_f32_16x16x32_bf16 v[96:99], v[186:189], v[208:211], v[96:99]
	v_mfma_f32_16x16x32_bf16 v[88:91], v[178:181], v[216:219], v[88:91]
	v_mfma_f32_16x16x32_bf16 v[80:83], v[186:189], v[216:219], v[80:83]
	v_mfma_f32_16x16x32_bf16 v[72:75], v[178:181], v[224:227], v[72:75]
	v_mfma_f32_16x16x32_bf16 v[64:67], v[186:189], v[224:227], v[64:67]
	v_mfma_f32_16x16x32_bf16 v[120:123], v[182:185], v[204:207], v[120:123]
	v_mfma_f32_16x16x32_bf16 v[112:115], v[190:193], v[204:207], v[112:115]
	v_mfma_f32_16x16x32_bf16 v[104:107], v[182:185], v[212:215], v[104:107]
	v_mfma_f32_16x16x32_bf16 v[96:99], v[190:193], v[212:215], v[96:99]
	v_mfma_f32_16x16x32_bf16 v[88:91], v[182:185], v[220:223], v[88:91]
	v_mfma_f32_16x16x32_bf16 v[80:83], v[190:193], v[220:223], v[80:83]
	v_mfma_f32_16x16x32_bf16 v[72:75], v[182:185], v[228:231], v[72:75]
	v_mfma_f32_16x16x32_bf16 v[64:67], v[190:193], v[228:231], v[64:67]
	s_setprio 0
	s_barrier
	s_add_i32 s56, s48, s39
	v_lshl_add_u64 v[194:195], s[4:5], 0, v[132:133]
	s_mov_b32 m0, s56
	ds_read_b128 v[198:201], v173 offset:16384
	ds_read_b128 v[204:207], v173 offset:17408
	ds_read_b128 v[208:211], v173 offset:18432
	ds_read_b128 v[212:215], v173 offset:19456
	ds_read_b128 v[216:219], v173 offset:20480
	ds_read_b128 v[220:223], v173 offset:21504
	ds_read_b128 v[224:227], v173 offset:22528
	ds_read_b128 v[228:231], v173 offset:23552
	global_load_lds_dwordx4 v132, s[4:5]
	s_add_i32 m0, s56, 0x2000
	s_add_u32 s56, s4, 0x40000
	v_lshl_add_u64 v[232:233], s[4:5], 0, v[128:129]
	s_addc_u32 s57, s5, 0
	s_add_i32 s58, s49, s39
	global_load_lds_dwordx4 v128, s[4:5]
	s_mov_b32 m0, s58
	v_lshl_add_u64 v[236:237], s[12:13], 0, v[130:131]
	global_load_lds_dwordx4 v132, s[56:57]
	s_add_i32 m0, s58, 0x2000
	s_nop 0
	global_load_lds_dwordx4 v128, s[56:57]
	v_lshl_add_u64 v[234:235], s[12:13], 0, v[134:135]
	s_mov_b32 m0, s41
	s_nop 0
	global_load_lds_dwordx4 v134, s[12:13]
	s_mov_b32 m0, s42
	s_nop 0
	global_load_lds_dwordx4 v130, s[12:13]
	s_waitcnt vmcnt(8)
	s_waitcnt lgkmcnt(0)
	s_barrier
	s_setprio 1
	s_waitcnt lgkmcnt(0)
	v_mfma_f32_16x16x32_bf16 v[60:63], v[146:149], v[198:201], v[60:63]
	v_mfma_f32_16x16x32_bf16 v[52:55], v[154:157], v[198:201], v[52:55]
	v_mfma_f32_16x16x32_bf16 v[44:47], v[146:149], v[208:211], v[44:47]
	v_mfma_f32_16x16x32_bf16 v[36:39], v[154:157], v[208:211], v[36:39]
	v_mfma_f32_16x16x32_bf16 v[28:31], v[146:149], v[216:219], v[28:31]
	v_mfma_f32_16x16x32_bf16 v[20:23], v[154:157], v[216:219], v[20:23]
	v_mfma_f32_16x16x32_bf16 v[12:15], v[146:149], v[224:227], v[12:15]
	v_mfma_f32_16x16x32_bf16 v[4:7], v[154:157], v[224:227], v[4:7]
	v_mfma_f32_16x16x32_bf16 v[60:63], v[150:153], v[204:207], v[60:63]
	v_mfma_f32_16x16x32_bf16 v[52:55], v[160:163], v[204:207], v[52:55]
	v_mfma_f32_16x16x32_bf16 v[44:47], v[150:153], v[212:215], v[44:47]
	v_mfma_f32_16x16x32_bf16 v[36:39], v[160:163], v[212:215], v[36:39]
	v_mfma_f32_16x16x32_bf16 v[28:31], v[150:153], v[220:223], v[28:31]
	v_mfma_f32_16x16x32_bf16 v[20:23], v[160:163], v[220:223], v[20:23]
	v_mfma_f32_16x16x32_bf16 v[12:15], v[150:153], v[228:231], v[12:15]
	v_mfma_f32_16x16x32_bf16 v[4:7], v[160:163], v[228:231], v[4:7]
	s_setprio 0
	s_setprio 1
	v_mfma_f32_16x16x32_bf16 v[56:59], v[178:181], v[198:201], v[56:59]
	v_mfma_f32_16x16x32_bf16 v[48:51], v[186:189], v[198:201], v[48:51]
	v_mfma_f32_16x16x32_bf16 v[40:43], v[178:181], v[208:211], v[40:43]
	v_mfma_f32_16x16x32_bf16 v[32:35], v[186:189], v[208:211], v[32:35]
	v_mfma_f32_16x16x32_bf16 v[24:27], v[178:181], v[216:219], v[24:27]
	v_mfma_f32_16x16x32_bf16 v[16:19], v[186:189], v[216:219], v[16:19]
	v_mfma_f32_16x16x32_bf16 v[8:11], v[178:181], v[224:227], v[8:11]
	v_mfma_f32_16x16x32_bf16 v[0:3], v[186:189], v[224:227], v[0:3]
	v_mfma_f32_16x16x32_bf16 v[56:59], v[182:185], v[204:207], v[56:59]
	v_mfma_f32_16x16x32_bf16 v[48:51], v[190:193], v[204:207], v[48:51]
	v_mfma_f32_16x16x32_bf16 v[40:43], v[182:185], v[212:215], v[40:43]
	v_mfma_f32_16x16x32_bf16 v[32:35], v[190:193], v[212:215], v[32:35]
	v_mfma_f32_16x16x32_bf16 v[24:27], v[182:185], v[220:223], v[24:27]
	v_mfma_f32_16x16x32_bf16 v[16:19], v[190:193], v[220:223], v[16:19]
	v_mfma_f32_16x16x32_bf16 v[8:11], v[182:185], v[228:231], v[8:11]
	v_mfma_f32_16x16x32_bf16 v[0:3], v[190:193], v[228:231], v[0:3]
	s_setprio 0
	s_barrier
	s_add_i32 s56, 0, 0x18000
	v_add_u32_e32 v158, s56, v165
	s_add_i32 s57, 0, 0x1c000
	ds_read_b128 v[146:149], v158
	ds_read_b128 v[150:153], v158 offset:1024
	ds_read_b128 v[154:157], v158 offset:2048
	ds_read_b128 v[160:163], v158 offset:3072
	v_add_u32_e32 v158, s57, v165
	ds_read_b128 v[178:181], v158
	ds_read_b128 v[182:185], v158 offset:1024
	ds_read_b128 v[186:189], v158 offset:2048
	ds_read_b128 v[190:193], v158 offset:3072
	s_add_u32 s12, s12, 0x40000
	s_addc_u32 s13, s13, 0
	s_mov_b32 m0, s43
	ds_read_b128 v[198:201], v173 offset:32768
	ds_read_b128 v[204:207], v173 offset:33792
	ds_read_b128 v[208:211], v173 offset:34816
	ds_read_b128 v[212:215], v173 offset:35840
	ds_read_b128 v[216:219], v173 offset:36864
	ds_read_b128 v[220:223], v173 offset:37888
	ds_read_b128 v[224:227], v173 offset:38912
	ds_read_b128 v[228:231], v173 offset:39936
	global_load_lds_dwordx4 v134, s[12:13]
	s_mov_b32 m0, s44
	s_nop 0
	global_load_lds_dwordx4 v130, s[12:13]
	s_waitcnt vmcnt(8)
	s_waitcnt lgkmcnt(0)
	s_barrier
	s_setprio 1
	s_waitcnt lgkmcnt(0)
	v_mfma_f32_16x16x32_bf16 v[124:127], v[146:149], v[198:201], v[124:127]
	v_mfma_f32_16x16x32_bf16 v[116:119], v[154:157], v[198:201], v[116:119]
	v_mfma_f32_16x16x32_bf16 v[108:111], v[146:149], v[208:211], v[108:111]
	v_mfma_f32_16x16x32_bf16 v[100:103], v[154:157], v[208:211], v[100:103]
	v_mfma_f32_16x16x32_bf16 v[92:95], v[146:149], v[216:219], v[92:95]
	v_mfma_f32_16x16x32_bf16 v[84:87], v[154:157], v[216:219], v[84:87]
	v_mfma_f32_16x16x32_bf16 v[76:79], v[146:149], v[224:227], v[76:79]
	v_mfma_f32_16x16x32_bf16 v[68:71], v[154:157], v[224:227], v[68:71]
	v_mfma_f32_16x16x32_bf16 v[124:127], v[150:153], v[204:207], v[124:127]
	v_mfma_f32_16x16x32_bf16 v[116:119], v[160:163], v[204:207], v[116:119]
	v_mfma_f32_16x16x32_bf16 v[108:111], v[150:153], v[212:215], v[108:111]
	v_mfma_f32_16x16x32_bf16 v[100:103], v[160:163], v[212:215], v[100:103]
	v_mfma_f32_16x16x32_bf16 v[92:95], v[150:153], v[220:223], v[92:95]
	v_mfma_f32_16x16x32_bf16 v[84:87], v[160:163], v[220:223], v[84:87]
	v_mfma_f32_16x16x32_bf16 v[76:79], v[150:153], v[228:231], v[76:79]
	v_mfma_f32_16x16x32_bf16 v[68:71], v[160:163], v[228:231], v[68:71]
	s_setprio 0
	s_setprio 1
	v_mfma_f32_16x16x32_bf16 v[120:123], v[178:181], v[198:201], v[120:123]
	v_mfma_f32_16x16x32_bf16 v[112:115], v[186:189], v[198:201], v[112:115]
	v_mfma_f32_16x16x32_bf16 v[104:107], v[178:181], v[208:211], v[104:107]
	v_mfma_f32_16x16x32_bf16 v[96:99], v[186:189], v[208:211], v[96:99]
	v_mfma_f32_16x16x32_bf16 v[88:91], v[178:181], v[216:219], v[88:91]
	v_mfma_f32_16x16x32_bf16 v[80:83], v[186:189], v[216:219], v[80:83]
	v_mfma_f32_16x16x32_bf16 v[72:75], v[178:181], v[224:227], v[72:75]
	v_mfma_f32_16x16x32_bf16 v[64:67], v[186:189], v[224:227], v[64:67]
	v_mfma_f32_16x16x32_bf16 v[120:123], v[182:185], v[204:207], v[120:123]
	v_mfma_f32_16x16x32_bf16 v[112:115], v[190:193], v[204:207], v[112:115]
	v_mfma_f32_16x16x32_bf16 v[104:107], v[182:185], v[212:215], v[104:107]
	v_mfma_f32_16x16x32_bf16 v[96:99], v[190:193], v[212:215], v[96:99]
	v_mfma_f32_16x16x32_bf16 v[88:91], v[182:185], v[220:223], v[88:91]
	v_mfma_f32_16x16x32_bf16 v[80:83], v[190:193], v[220:223], v[80:83]
	v_mfma_f32_16x16x32_bf16 v[72:75], v[182:185], v[228:231], v[72:75]
	v_mfma_f32_16x16x32_bf16 v[64:67], v[190:193], v[228:231], v[64:67]
	s_setprio 0
	s_barrier
	s_add_i32 s12, s56, s39
	v_lshl_add_u64 v[194:195], v[194:195], 0, s[24:25]
	s_mov_b32 m0, s12
	ds_read_b128 v[198:201], v173 offset:49152
	ds_read_b128 v[204:207], v173 offset:50176
	ds_read_b128 v[208:211], v173 offset:51200
	ds_read_b128 v[212:215], v173 offset:52224
	ds_read_b128 v[216:219], v173 offset:53248
	ds_read_b128 v[220:223], v173 offset:54272
	ds_read_b128 v[224:227], v173 offset:55296
	ds_read_b128 v[228:231], v173 offset:56320
	global_load_lds_dwordx4 v[194:195], off
	s_add_i32 m0, s12, 0x2000
	s_add_u32 s4, s4, 0x40080
	v_lshl_add_u64 v[194:195], v[232:233], 0, s[24:25]
	s_addc_u32 s5, s5, 0
	s_add_i32 s12, s57, s39
	global_load_lds_dwordx4 v[194:195], off
	s_mov_b32 m0, s12
	s_nop 0
	global_load_lds_dwordx4 v132, s[4:5]
	s_add_i32 m0, s12, 0x2000
	s_nop 0
	global_load_lds_dwordx4 v128, s[4:5]
	v_lshl_add_u64 v[194:195], v[234:235], 0, s[24:25]
	s_mov_b32 m0, s46
	s_nop 0
	global_load_lds_dwordx4 v[194:195], off
	v_lshl_add_u64 v[194:195], v[236:237], 0, s[24:25]
	s_mov_b32 m0, s47
	s_nop 0
	global_load_lds_dwordx4 v[194:195], off
	s_waitcnt vmcnt(8)
	s_waitcnt lgkmcnt(0)
	s_barrier
	s_setprio 1
	s_waitcnt lgkmcnt(0)
	v_mfma_f32_16x16x32_bf16 v[60:63], v[146:149], v[198:201], v[60:63]
	v_mfma_f32_16x16x32_bf16 v[52:55], v[154:157], v[198:201], v[52:55]
	v_mfma_f32_16x16x32_bf16 v[44:47], v[146:149], v[208:211], v[44:47]
	v_mfma_f32_16x16x32_bf16 v[36:39], v[154:157], v[208:211], v[36:39]
	v_mfma_f32_16x16x32_bf16 v[28:31], v[146:149], v[216:219], v[28:31]
	v_mfma_f32_16x16x32_bf16 v[20:23], v[154:157], v[216:219], v[20:23]
	v_mfma_f32_16x16x32_bf16 v[12:15], v[146:149], v[224:227], v[12:15]
	v_mfma_f32_16x16x32_bf16 v[4:7], v[154:157], v[224:227], v[4:7]
	v_mfma_f32_16x16x32_bf16 v[60:63], v[150:153], v[204:207], v[60:63]
	v_mfma_f32_16x16x32_bf16 v[52:55], v[160:163], v[204:207], v[52:55]
	v_mfma_f32_16x16x32_bf16 v[44:47], v[150:153], v[212:215], v[44:47]
	v_mfma_f32_16x16x32_bf16 v[36:39], v[160:163], v[212:215], v[36:39]
	v_mfma_f32_16x16x32_bf16 v[28:31], v[150:153], v[220:223], v[28:31]
	v_mfma_f32_16x16x32_bf16 v[20:23], v[160:163], v[220:223], v[20:23]
	v_mfma_f32_16x16x32_bf16 v[12:15], v[150:153], v[228:231], v[12:15]
	v_mfma_f32_16x16x32_bf16 v[4:7], v[160:163], v[228:231], v[4:7]
	s_setprio 0
	s_setprio 1
	v_mfma_f32_16x16x32_bf16 v[56:59], v[178:181], v[198:201], v[56:59]
	v_mfma_f32_16x16x32_bf16 v[48:51], v[186:189], v[198:201], v[48:51]
	v_mfma_f32_16x16x32_bf16 v[40:43], v[178:181], v[208:211], v[40:43]
	v_mfma_f32_16x16x32_bf16 v[32:35], v[186:189], v[208:211], v[32:35]
	v_mfma_f32_16x16x32_bf16 v[24:27], v[178:181], v[216:219], v[24:27]
	v_mfma_f32_16x16x32_bf16 v[16:19], v[186:189], v[216:219], v[16:19]
	v_mfma_f32_16x16x32_bf16 v[8:11], v[178:181], v[224:227], v[8:11]
	v_mfma_f32_16x16x32_bf16 v[0:3], v[186:189], v[224:227], v[0:3]
	v_mfma_f32_16x16x32_bf16 v[56:59], v[182:185], v[204:207], v[56:59]
	v_mfma_f32_16x16x32_bf16 v[48:51], v[190:193], v[204:207], v[48:51]
	v_mfma_f32_16x16x32_bf16 v[40:43], v[182:185], v[212:215], v[40:43]
	v_mfma_f32_16x16x32_bf16 v[32:35], v[190:193], v[212:215], v[32:35]
	v_mfma_f32_16x16x32_bf16 v[24:27], v[182:185], v[220:223], v[24:27]
	v_mfma_f32_16x16x32_bf16 v[16:19], v[190:193], v[220:223], v[16:19]
	v_mfma_f32_16x16x32_bf16 v[8:11], v[182:185], v[228:231], v[8:11]
	v_mfma_f32_16x16x32_bf16 v[0:3], v[190:193], v[228:231], v[0:3]
	s_setprio 0
	s_barrier
	s_add_i32 s55, s55, 2
	s_add_u32 s10, s10, 0x100
	s_addc_u32 s11, s11, 0
	s_add_u32 s53, s53, 0x100
	s_addc_u32 s54, s54, 0
	s_cmp_gt_u32 s55, 13
	s_cbranch_scc0 .LBB0_1048
	s_and_b64 vcc, exec, s[26:27]
	s_cbranch_vccz .LBB0_1051
	s_barrier

.LBB0_1124:
	ds_read_b128 v[128:131], v189
	ds_read_b128 v[132:135], v189 offset:1024
	ds_read_b128 v[136:139], v189 offset:2048
	ds_read_b128 v[140:143], v189 offset:3072
	ds_read_b128 v[144:147], v190
	ds_read_b128 v[148:151], v190 offset:1024
	ds_read_b128 v[168:171], v190 offset:2048
	ds_read_b128 v[172:175], v190 offset:3072
	s_add_u32 s34, s30, 0x100
	s_addc_u32 s35, s31, 0
	s_cmp_eq_u32 s56, 40
	s_cselect_b32 s39, s9, s35
	s_cselect_b32 s38, s8, s34
	s_cselect_b32 s37, s29, s55
	s_cselect_b32 s36, s28, s54
	s_add_i32 m0, s42, 0xc000
	ds_read_b128 v[176:179], v191
	ds_read_b128 v[180:183], v191 offset:1024
	ds_read_b128 v[192:195], v191 offset:2048
	ds_read_b128 v[198:201], v191 offset:3072
	ds_read_b128 v[204:207], v191 offset:4096
	ds_read_b128 v[208:211], v191 offset:5120
	ds_read_b128 v[212:215], v191 offset:6144
	ds_read_b128 v[216:219], v191 offset:7168
	global_load_lds_dwordx4 v160, s[30:31]
	s_add_i32 m0, s42, 0xe000
	s_nop 0
	global_load_lds_dwordx4 v162, s[30:31]
	s_waitcnt vmcnt(8)
	s_waitcnt lgkmcnt(0)
	s_barrier
	s_setprio 1
	s_waitcnt lgkmcnt(0)
	v_mfma_f32_16x16x32_bf16 v[124:127], v[128:131], v[176:179], v[124:127]
	v_mfma_f32_16x16x32_bf16 v[120:123], v[136:139], v[176:179], v[120:123]
	v_mfma_f32_16x16x32_bf16 v[108:111], v[128:131], v[192:195], v[108:111]
	v_mfma_f32_16x16x32_bf16 v[104:107], v[136:139], v[192:195], v[104:107]
	v_mfma_f32_16x16x32_bf16 v[92:95], v[128:131], v[204:207], v[92:95]
	v_mfma_f32_16x16x32_bf16 v[88:91], v[136:139], v[204:207], v[88:91]
	v_mfma_f32_16x16x32_bf16 v[76:79], v[128:131], v[212:215], v[76:79]
	v_mfma_f32_16x16x32_bf16 v[72:75], v[136:139], v[212:215], v[72:75]
	v_mfma_f32_16x16x32_bf16 v[124:127], v[132:135], v[180:183], v[124:127]
	v_mfma_f32_16x16x32_bf16 v[120:123], v[140:143], v[180:183], v[120:123]
	v_mfma_f32_16x16x32_bf16 v[108:111], v[132:135], v[198:201], v[108:111]
	v_mfma_f32_16x16x32_bf16 v[104:107], v[140:143], v[198:201], v[104:107]
	v_mfma_f32_16x16x32_bf16 v[92:95], v[132:135], v[208:211], v[92:95]
	v_mfma_f32_16x16x32_bf16 v[88:91], v[140:143], v[208:211], v[88:91]
	v_mfma_f32_16x16x32_bf16 v[76:79], v[132:135], v[216:219], v[76:79]
	v_mfma_f32_16x16x32_bf16 v[72:75], v[140:143], v[216:219], v[72:75]
	s_setprio 0
	s_setprio 1
	v_mfma_f32_16x16x32_bf16 v[116:119], v[144:147], v[176:179], v[116:119]
	v_mfma_f32_16x16x32_bf16 v[112:115], v[168:171], v[176:179], v[112:115]
	v_mfma_f32_16x16x32_bf16 v[100:103], v[144:147], v[192:195], v[100:103]
	v_mfma_f32_16x16x32_bf16 v[96:99], v[168:171], v[192:195], v[96:99]
	v_mfma_f32_16x16x32_bf16 v[84:87], v[144:147], v[204:207], v[84:87]
	v_mfma_f32_16x16x32_bf16 v[80:83], v[168:171], v[204:207], v[80:83]
	v_mfma_f32_16x16x32_bf16 v[68:71], v[144:147], v[212:215], v[68:71]
	v_mfma_f32_16x16x32_bf16 v[64:67], v[168:171], v[212:215], v[64:67]
	v_mfma_f32_16x16x32_bf16 v[116:119], v[148:151], v[180:183], v[116:119]
	v_mfma_f32_16x16x32_bf16 v[112:115], v[172:175], v[180:183], v[112:115]
	v_mfma_f32_16x16x32_bf16 v[100:103], v[148:151], v[198:201], v[100:103]
	v_mfma_f32_16x16x32_bf16 v[96:99], v[172:175], v[198:201], v[96:99]
	v_mfma_f32_16x16x32_bf16 v[84:87], v[148:151], v[208:211], v[84:87]
	v_mfma_f32_16x16x32_bf16 v[80:83], v[172:175], v[208:211], v[80:83]
	v_mfma_f32_16x16x32_bf16 v[68:71], v[148:151], v[216:219], v[68:71]
	v_mfma_f32_16x16x32_bf16 v[64:67], v[172:175], v[216:219], v[64:67]
	s_setprio 0
	s_barrier
	s_add_i32 s30, s48, s41
	v_lshl_add_u64 v[184:185], s[36:37], 0, v[154:155]
	s_mov_b32 m0, s30
	ds_read_b128 v[176:179], v191 offset:16384
	ds_read_b128 v[180:183], v191 offset:17408
	ds_read_b128 v[192:195], v191 offset:18432
	ds_read_b128 v[198:201], v191 offset:19456
	ds_read_b128 v[204:207], v191 offset:20480
	ds_read_b128 v[208:211], v191 offset:21504
	ds_read_b128 v[212:215], v191 offset:22528
	ds_read_b128 v[216:219], v191 offset:23552
	global_load_lds_dwordx4 v154, s[36:37]
	s_add_i32 m0, s30, 0x2000
	s_add_u32 s30, s36, 0xb0000
	v_lshl_add_u64 v[220:221], s[36:37], 0, v[158:159]
	s_addc_u32 s31, s37, 0
	s_add_i32 s57, s49, s41
	global_load_lds_dwordx4 v158, s[36:37]
	s_mov_b32 m0, s57
	v_lshl_add_u64 v[224:225], s[38:39], 0, v[156:157]
	global_load_lds_dwordx4 v154, s[30:31]
	s_add_i32 m0, s57, 0x2000
	s_nop 0
	global_load_lds_dwordx4 v158, s[30:31]
	v_lshl_add_u64 v[222:223], s[38:39], 0, v[152:153]
	s_mov_b32 m0, s42
	s_nop 0
	global_load_lds_dwordx4 v152, s[38:39]
	s_mov_b32 m0, s33
	s_nop 0
	global_load_lds_dwordx4 v156, s[38:39]
	s_waitcnt vmcnt(8)
	s_waitcnt lgkmcnt(0)
	s_barrier
	s_setprio 1
	s_waitcnt lgkmcnt(0)
	v_mfma_f32_16x16x32_bf16 v[60:63], v[128:131], v[176:179], v[60:63]
	v_mfma_f32_16x16x32_bf16 v[56:59], v[136:139], v[176:179], v[56:59]
	v_mfma_f32_16x16x32_bf16 v[44:47], v[128:131], v[192:195], v[44:47]
	v_mfma_f32_16x16x32_bf16 v[40:43], v[136:139], v[192:195], v[40:43]
	v_mfma_f32_16x16x32_bf16 v[28:31], v[128:131], v[204:207], v[28:31]
	v_mfma_f32_16x16x32_bf16 v[24:27], v[136:139], v[204:207], v[24:27]
	v_mfma_f32_16x16x32_bf16 v[12:15], v[128:131], v[212:215], v[12:15]
	v_mfma_f32_16x16x32_bf16 v[8:11], v[136:139], v[212:215], v[8:11]
	v_mfma_f32_16x16x32_bf16 v[60:63], v[132:135], v[180:183], v[60:63]
	v_mfma_f32_16x16x32_bf16 v[56:59], v[140:143], v[180:183], v[56:59]
	v_mfma_f32_16x16x32_bf16 v[44:47], v[132:135], v[198:201], v[44:47]
	v_mfma_f32_16x16x32_bf16 v[40:43], v[140:143], v[198:201], v[40:43]
	v_mfma_f32_16x16x32_bf16 v[28:31], v[132:135], v[208:211], v[28:31]
	v_mfma_f32_16x16x32_bf16 v[24:27], v[140:143], v[208:211], v[24:27]
	v_mfma_f32_16x16x32_bf16 v[12:15], v[132:135], v[216:219], v[12:15]
	v_mfma_f32_16x16x32_bf16 v[8:11], v[140:143], v[216:219], v[8:11]
	s_setprio 0
	s_setprio 1
	v_mfma_f32_16x16x32_bf16 v[52:55], v[144:147], v[176:179], v[52:55]
	v_mfma_f32_16x16x32_bf16 v[48:51], v[168:171], v[176:179], v[48:51]
	v_mfma_f32_16x16x32_bf16 v[36:39], v[144:147], v[192:195], v[36:39]
	v_mfma_f32_16x16x32_bf16 v[32:35], v[168:171], v[192:195], v[32:35]
	v_mfma_f32_16x16x32_bf16 v[20:23], v[144:147], v[204:207], v[20:23]
	v_mfma_f32_16x16x32_bf16 v[16:19], v[168:171], v[204:207], v[16:19]
	v_mfma_f32_16x16x32_bf16 v[4:7], v[144:147], v[212:215], v[4:7]
	v_mfma_f32_16x16x32_bf16 v[0:3], v[168:171], v[212:215], v[0:3]
	v_mfma_f32_16x16x32_bf16 v[52:55], v[148:151], v[180:183], v[52:55]
	v_mfma_f32_16x16x32_bf16 v[48:51], v[172:175], v[180:183], v[48:51]
	v_mfma_f32_16x16x32_bf16 v[36:39], v[148:151], v[198:201], v[36:39]
	v_mfma_f32_16x16x32_bf16 v[32:35], v[172:175], v[198:201], v[32:35]
	v_mfma_f32_16x16x32_bf16 v[20:23], v[148:151], v[208:211], v[20:23]
	v_mfma_f32_16x16x32_bf16 v[16:19], v[172:175], v[208:211], v[16:19]
	v_mfma_f32_16x16x32_bf16 v[4:7], v[148:151], v[216:219], v[4:7]
	v_mfma_f32_16x16x32_bf16 v[0:3], v[172:175], v[216:219], v[0:3]
	s_setprio 0
	s_barrier
	s_add_i32 s57, 0, 0x18000
	s_add_i32 s58, 0, 0x1c000
	v_add_u32_e32 v140, s57, v187
	v_add_u32_e32 v172, s58, v187
	ds_read_b128 v[128:131], v140
	ds_read_b128 v[132:135], v140 offset:1024
	ds_read_b128 v[136:139], v140 offset:2048
	ds_read_b128 v[140:143], v140 offset:3072
	ds_read_b128 v[144:147], v172
	ds_read_b128 v[148:151], v172 offset:1024
	ds_read_b128 v[168:171], v172 offset:2048
	ds_read_b128 v[172:175], v172 offset:3072
	s_add_u32 s30, s38, 0xb0000
	s_addc_u32 s31, s39, 0
	s_mov_b32 m0, s43
	ds_read_b128 v[176:179], v191 offset:32768
	ds_read_b128 v[180:183], v191 offset:33792
	ds_read_b128 v[192:195], v191 offset:34816
	ds_read_b128 v[198:201], v191 offset:35840
	ds_read_b128 v[204:207], v191 offset:36864
	ds_read_b128 v[208:211], v191 offset:37888
	ds_read_b128 v[212:215], v191 offset:38912
	ds_read_b128 v[216:219], v191 offset:39936
	global_load_lds_dwordx4 v152, s[30:31]
	s_mov_b32 m0, s44
	s_nop 0
	global_load_lds_dwordx4 v156, s[30:31]
	s_waitcnt vmcnt(8)
	s_waitcnt lgkmcnt(0)
	s_barrier
	s_setprio 1
	s_waitcnt lgkmcnt(0)
	v_mfma_f32_16x16x32_bf16 v[124:127], v[128:131], v[176:179], v[124:127]
	v_mfma_f32_16x16x32_bf16 v[120:123], v[136:139], v[176:179], v[120:123]
	v_mfma_f32_16x16x32_bf16 v[108:111], v[128:131], v[192:195], v[108:111]
	v_mfma_f32_16x16x32_bf16 v[104:107], v[136:139], v[192:195], v[104:107]
	v_mfma_f32_16x16x32_bf16 v[92:95], v[128:131], v[204:207], v[92:95]
	v_mfma_f32_16x16x32_bf16 v[88:91], v[136:139], v[204:207], v[88:91]
	v_mfma_f32_16x16x32_bf16 v[76:79], v[128:131], v[212:215], v[76:79]
	v_mfma_f32_16x16x32_bf16 v[72:75], v[136:139], v[212:215], v[72:75]
	v_mfma_f32_16x16x32_bf16 v[124:127], v[132:135], v[180:183], v[124:127]
	v_mfma_f32_16x16x32_bf16 v[120:123], v[140:143], v[180:183], v[120:123]
	v_mfma_f32_16x16x32_bf16 v[108:111], v[132:135], v[198:201], v[108:111]
	v_mfma_f32_16x16x32_bf16 v[104:107], v[140:143], v[198:201], v[104:107]
	v_mfma_f32_16x16x32_bf16 v[92:95], v[132:135], v[208:211], v[92:95]
	v_mfma_f32_16x16x32_bf16 v[88:91], v[140:143], v[208:211], v[88:91]
	v_mfma_f32_16x16x32_bf16 v[76:79], v[132:135], v[216:219], v[76:79]
	v_mfma_f32_16x16x32_bf16 v[72:75], v[140:143], v[216:219], v[72:75]
	s_setprio 0
	s_setprio 1
	v_mfma_f32_16x16x32_bf16 v[116:119], v[144:147], v[176:179], v[116:119]
	v_mfma_f32_16x16x32_bf16 v[112:115], v[168:171], v[176:179], v[112:115]
	v_mfma_f32_16x16x32_bf16 v[100:103], v[144:147], v[192:195], v[100:103]
	v_mfma_f32_16x16x32_bf16 v[96:99], v[168:171], v[192:195], v[96:99]
	v_mfma_f32_16x16x32_bf16 v[84:87], v[144:147], v[204:207], v[84:87]
	v_mfma_f32_16x16x32_bf16 v[80:83], v[168:171], v[204:207], v[80:83]
	v_mfma_f32_16x16x32_bf16 v[68:71], v[144:147], v[212:215], v[68:71]
	v_mfma_f32_16x16x32_bf16 v[64:67], v[168:171], v[212:215], v[64:67]
	v_mfma_f32_16x16x32_bf16 v[116:119], v[148:151], v[180:183], v[116:119]
	v_mfma_f32_16x16x32_bf16 v[112:115], v[172:175], v[180:183], v[112:115]
	v_mfma_f32_16x16x32_bf16 v[100:103], v[148:151], v[198:201], v[100:103]
	v_mfma_f32_16x16x32_bf16 v[96:99], v[172:175], v[198:201], v[96:99]
	v_mfma_f32_16x16x32_bf16 v[84:87], v[148:151], v[208:211], v[84:87]
	v_mfma_f32_16x16x32_bf16 v[80:83], v[172:175], v[208:211], v[80:83]
	v_mfma_f32_16x16x32_bf16 v[68:71], v[148:151], v[216:219], v[68:71]
	v_mfma_f32_16x16x32_bf16 v[64:67], v[172:175], v[216:219], v[64:67]
	s_setprio 0
	s_barrier
	s_add_i32 s30, s57, s41
	v_lshl_add_u64 v[184:185], v[184:185], 0, s[24:25]
	s_mov_b32 m0, s30
	ds_read_b128 v[176:179], v191 offset:49152
	ds_read_b128 v[180:183], v191 offset:50176
	ds_read_b128 v[192:195], v191 offset:51200
	ds_read_b128 v[198:201], v191 offset:52224
	ds_read_b128 v[204:207], v191 offset:53248
	ds_read_b128 v[208:211], v191 offset:54272
	ds_read_b128 v[212:215], v191 offset:55296
	ds_read_b128 v[216:219], v191 offset:56320
	global_load_lds_dwordx4 v[184:185], off
	s_add_i32 m0, s30, 0x2000
	s_add_u32 s30, s36, 0xb0080
	v_lshl_add_u64 v[184:185], v[220:221], 0, s[24:25]
	s_addc_u32 s31, s37, 0
	s_add_i32 s36, s58, s41
	global_load_lds_dwordx4 v[184:185], off
	s_mov_b32 m0, s36
	s_nop 0
	global_load_lds_dwordx4 v154, s[30:31]
	s_add_i32 m0, s36, 0x2000
	s_nop 0
	global_load_lds_dwordx4 v158, s[30:31]
	v_lshl_add_u64 v[184:185], v[222:223], 0, s[24:25]
	s_mov_b32 m0, s46
	s_nop 0
	global_load_lds_dwordx4 v[184:185], off
	v_lshl_add_u64 v[184:185], v[224:225], 0, s[24:25]
	s_mov_b32 m0, s47
	s_nop 0
	global_load_lds_dwordx4 v[184:185], off
	s_waitcnt vmcnt(8)
	s_waitcnt lgkmcnt(0)
	s_barrier
	s_setprio 1
	s_waitcnt lgkmcnt(0)
	v_mfma_f32_16x16x32_bf16 v[60:63], v[128:131], v[176:179], v[60:63]
	v_mfma_f32_16x16x32_bf16 v[56:59], v[136:139], v[176:179], v[56:59]
	v_mfma_f32_16x16x32_bf16 v[44:47], v[128:131], v[192:195], v[44:47]
	v_mfma_f32_16x16x32_bf16 v[40:43], v[136:139], v[192:195], v[40:43]
	v_mfma_f32_16x16x32_bf16 v[28:31], v[128:131], v[204:207], v[28:31]
	v_mfma_f32_16x16x32_bf16 v[24:27], v[136:139], v[204:207], v[24:27]
	v_mfma_f32_16x16x32_bf16 v[12:15], v[128:131], v[212:215], v[12:15]
	v_mfma_f32_16x16x32_bf16 v[8:11], v[136:139], v[212:215], v[8:11]
	v_mfma_f32_16x16x32_bf16 v[60:63], v[132:135], v[180:183], v[60:63]
	v_mfma_f32_16x16x32_bf16 v[56:59], v[140:143], v[180:183], v[56:59]
	v_mfma_f32_16x16x32_bf16 v[44:47], v[132:135], v[198:201], v[44:47]
	v_mfma_f32_16x16x32_bf16 v[40:43], v[140:143], v[198:201], v[40:43]
	v_mfma_f32_16x16x32_bf16 v[28:31], v[132:135], v[208:211], v[28:31]
	v_mfma_f32_16x16x32_bf16 v[24:27], v[140:143], v[208:211], v[24:27]
	v_mfma_f32_16x16x32_bf16 v[12:15], v[132:135], v[216:219], v[12:15]
	v_mfma_f32_16x16x32_bf16 v[8:11], v[140:143], v[216:219], v[8:11]
	s_setprio 0
	s_setprio 1
	v_mfma_f32_16x16x32_bf16 v[52:55], v[144:147], v[176:179], v[52:55]
	v_mfma_f32_16x16x32_bf16 v[48:51], v[168:171], v[176:179], v[48:51]
	v_mfma_f32_16x16x32_bf16 v[36:39], v[144:147], v[192:195], v[36:39]
	v_mfma_f32_16x16x32_bf16 v[32:35], v[168:171], v[192:195], v[32:35]
	v_mfma_f32_16x16x32_bf16 v[20:23], v[144:147], v[204:207], v[20:23]
	v_mfma_f32_16x16x32_bf16 v[16:19], v[168:171], v[204:207], v[16:19]
	v_mfma_f32_16x16x32_bf16 v[4:7], v[144:147], v[212:215], v[4:7]
	v_mfma_f32_16x16x32_bf16 v[0:3], v[168:171], v[212:215], v[0:3]
	v_mfma_f32_16x16x32_bf16 v[52:55], v[148:151], v[180:183], v[52:55]
	v_mfma_f32_16x16x32_bf16 v[48:51], v[172:175], v[180:183], v[48:51]
	v_mfma_f32_16x16x32_bf16 v[36:39], v[148:151], v[198:201], v[36:39]
	v_mfma_f32_16x16x32_bf16 v[32:35], v[172:175], v[198:201], v[32:35]
	v_mfma_f32_16x16x32_bf16 v[20:23], v[148:151], v[208:211], v[20:23]
	v_mfma_f32_16x16x32_bf16 v[16:19], v[172:175], v[208:211], v[16:19]
	v_mfma_f32_16x16x32_bf16 v[4:7], v[148:151], v[216:219], v[4:7]
	v_mfma_f32_16x16x32_bf16 v[0:3], v[172:175], v[216:219], v[0:3]
	s_setprio 0
	s_barrier
	s_add_i32 s56, s56, 2
	s_add_u32 s54, s54, 0x100
	s_addc_u32 s55, s55, 0
	s_cmp_gt_u32 s56, 41
	s_mov_b64 s[30:31], s[34:35]
	s_cbranch_scc0 .LBB0_1124
	s_and_b64 vcc, exec, s[26:27]
	s_cbranch_vccz .LBB0_1127
	s_barrier
